# v6 + row-max chain trims (self-max, add-zero removed), MLA loop-tail VALU moved before the barrier and packed adds split, G epilogue counted waits relaxed
# speedup vs baseline: 1.0020x; 1.0020x over previous
; #define LAS __attribute__((address_space(3)))
; __device__ __forceinline__ int crow(int r, int hi) { return (r & 3) + 8 * (r >> 2) + 4 * hi; }
; __device__ __forceinline__ void add_bias(f32x16& p0, f32x16& p1, const LAS float* tbl, int kq, int hi) {
; #pragma unroll
;   for (int r = 0; r < 16; ++r) { const int rel = kq + crow(r, hi);
;     p0[r] += tbl[min(max(rel, -128), 128) + 128]; p1[r] += tbl[min(max(rel + 32, -128), 128) + 128]; }
; }
; __device__ __forceinline__ void attn_pass_dv256(const bf16_t* __restrict__ Qb, const bf16_t* __restrict__ Kh, const bf16_t* __restrict__ Vh, int qpos0,
;                                                 LAS unsigned char* lds, f32x16 (&o)[8], float& l_out, int wave_) {
;     ...
;     { const LAS unsigned char* Ks = K_lds + sl * SHM_K; p0 = f32x16{}; p1 = f32x16{};
; #pragma unroll
;       for (int d0 = 0; d0 < 8; ++d0) { const int cb = (d0 * 16 + hi * 8) * 2;
;         const bf16x8 b0 = *(const LAS bf16x8*)(Ks + KSWZ(r32, cb)), b1 = *(const LAS bf16x8*)(Ks + KSWZ(32 + r32, cb));
;         const bf16x8 q = d0 < 4 ? qr[d0 & 3] : *(const LAS bf16x8*)(qf + ((d0 - 4) * 64 + lane) * 16);
;         p0 = __builtin_amdgcn_mfma_f32_32x32x16_bf16(b0, q, p0, 0, 0, 0); p1 = __builtin_amdgcn_mfma_f32_32x32x16_bf16(b1, q, p1, 0, 0, 0); } }
;     { const int dd = j * KVBLK - qw0;
;       if (dd <= -191 || dd >= 159) { cadd = (dd < 0) ? tbl[0] : tbl[256]; partialSM(p0, p1, m_reg, mn, al, cadd); }
;       else { add_bias(p0, p1, tbl, j * KVBLK - qme, hi); partialSM(p0, p1, m_reg, mn, al, 0.f); } }
.LBB0_374:
	s_and_b32 s47, s45, 1
	s_lshl_b32 s46, s47, 14
	v_add_u32_e32 v182, s46, v237
	v_add_u32_e32 v132, v182, v239
	ds_read_b128 v[128:131], v132
	ds_read_b128 v[144:147], v132 offset:8192
	v_add_u32_e32 v183, v182, v240
	ds_read_b128 v[178:181], v183
	ds_read_b128 v[192:195], v183 offset:8192
	v_add_u32_e32 v183, v182, v241
	ds_read_b128 v[200:203], v183
	ds_read_b128 v[204:207], v183 offset:8192
	s_add_i32 s16, s30, s37
	s_add_i32 s12, s16, 0xffffff61
	s_mov_b64 s[24:25], -1
	s_cmp_gt_u32 s12, 0xfffffea2
	s_waitcnt lgkmcnt(5)
	v_mfma_f32_32x32x16_bf16 v[128:143], v[128:131], v[160:163], 0
	s_waitcnt lgkmcnt(4)
	v_mfma_f32_32x32x16_bf16 v[144:159], v[144:147], v[160:163], 0
	s_waitcnt lgkmcnt(3)
	v_mfma_f32_32x32x16_bf16 v[128:143], v[178:181], v[168:171], v[128:143]
	s_waitcnt lgkmcnt(2)
	v_mfma_f32_32x32x16_bf16 v[144:159], v[192:195], v[168:171], v[144:159]
	v_add_u32_e32 v183, v182, v242
	ds_read_b128 v[178:181], v183
	ds_read_b128 v[192:195], v183 offset:8192
	s_waitcnt lgkmcnt(3)
	v_mfma_f32_32x32x16_bf16 v[128:143], v[200:203], v[172:175], v[128:143]
	s_waitcnt lgkmcnt(2)
	v_mfma_f32_32x32x16_bf16 v[144:159], v[204:207], v[172:175], v[144:159]
	v_add_u32_e32 v183, v182, v243
	ds_read_b128 v[200:203], v183
	ds_read_b128 v[204:207], v183 offset:8192
	ds_read_b128 v[208:211], v234
	s_waitcnt lgkmcnt(4)
	v_mfma_f32_32x32x16_bf16 v[128:143], v[178:181], v[164:167], v[128:143]
	s_waitcnt lgkmcnt(3)
	v_mfma_f32_32x32x16_bf16 v[144:159], v[192:195], v[164:167], v[144:159]
	v_add_u32_e32 v183, v182, v244
	ds_read_b128 v[178:181], v183
	ds_read_b128 v[192:195], v183 offset:8192
	ds_read_b128 v[196:199], v234 offset:1024
	s_waitcnt lgkmcnt(3)
	v_mfma_f32_32x32x16_bf16 v[128:143], v[200:203], v[208:211], v[128:143]
	v_mfma_f32_32x32x16_bf16 v[144:159], v[204:207], v[208:211], v[144:159]
	v_add_u32_e32 v183, v182, v245
	ds_read_b128 v[200:203], v183
	ds_read_b128 v[204:207], v183 offset:8192
	ds_read_b128 v[208:211], v234 offset:2048
	s_waitcnt lgkmcnt(3)
	v_mfma_f32_32x32x16_bf16 v[128:143], v[178:181], v[196:199], v[128:143]
	v_mfma_f32_32x32x16_bf16 v[144:159], v[192:195], v[196:199], v[144:159]
	v_add_u32_e32 v182, v182, v246
	ds_read_b128 v[178:181], v182
	ds_read_b128 v[192:195], v182 offset:8192
	ds_read_b128 v[196:199], v234 offset:3072
	s_waitcnt lgkmcnt(3)
	v_mfma_f32_32x32x16_bf16 v[128:143], v[200:203], v[208:211], v[128:143]
	v_mfma_f32_32x32x16_bf16 v[144:159], v[204:207], v[208:211], v[144:159]
	s_waitcnt lgkmcnt(0)
	v_mfma_f32_32x32x16_bf16 v[128:143], v[178:181], v[196:199], v[128:143]
	v_mfma_f32_32x32x16_bf16 v[144:159], v[192:195], v[196:199], v[144:159]
	s_cbranch_scc0 .LBB0_376
	v_add_u32_e32 v190, s37, v248
	v_add_u32_e32 v182, 2, v190
	s_add_i32 s12, 0, 0x18800
	v_med3_i32 v183, v182, s50, v228
	v_med3_i32 v182, v182, s51, v229
	v_lshl_add_u32 v194, v182, 2, s12
	v_add_u32_e32 v182, 3, v190
	v_med3_i32 v178, v190, s50, v228
	v_med3_i32 v179, v190, s51, v229
	v_add_u32_e32 v180, 1, v190
	v_lshl_add_u32 v191, v183, 2, s12
	v_med3_i32 v183, v182, s50, v228
	v_med3_i32 v182, v182, s51, v229
	v_lshl_add_u32 v178, v178, 2, s12
	v_lshl_add_u32 v179, v179, 2, s12
	v_med3_i32 v181, v180, s50, v228
	v_med3_i32 v180, v180, s51, v229
	v_lshl_add_u32 v193, v183, 2, s12
	v_lshl_add_u32 v195, v182, 2, s12
	v_lshl_add_u32 v181, v181, 2, s12
	v_lshl_add_u32 v180, v180, 2, s12
	ds_read_b32 v178, v178 offset:512
	ds_read_b32 v182, v179 offset:640
	ds_read_b32 v179, v181 offset:512
	ds_read_b32 v183, v180 offset:640
	ds_read_b32 v192, v191 offset:512
	ds_read_b32 v193, v193 offset:512
	ds_read_b32 v195, v195 offset:640
	ds_read_b32 v194, v194 offset:640
	s_waitcnt lgkmcnt(5)
	v_pk_add_f32 v[180:181], v[128:129], v[178:179]
	s_waitcnt lgkmcnt(4)
	v_pk_add_f32 v[178:179], v[144:145], v[182:183]
	s_waitcnt lgkmcnt(2)
	v_pk_add_f32 v[182:183], v[130:131], v[192:193]
	v_add_u32_e32 v193, 9, v190
	v_med3_i32 v196, v193, s50, v228
	v_lshl_add_u32 v197, v196, 2, s12
	v_add_u32_e32 v196, 10, v190
	v_med3_i32 v198, v196, s50, v228
	v_med3_i32 v196, v196, s51, v229
	v_add_u32_e32 v191, 8, v190
	v_lshl_add_u32 v199, v196, 2, s12
	v_add_u32_e32 v196, 11, v190
	v_med3_i32 v192, v191, s50, v228
	v_med3_i32 v200, v196, s50, v228
	v_med3_i32 v196, v196, s51, v229
	v_lshl_add_u32 v192, v192, 2, s12
	v_med3_i32 v191, v191, s51, v229
	v_med3_i32 v193, v193, s51, v229
	v_lshl_add_u32 v203, v200, 2, s12
	v_lshl_add_u32 v205, v196, 2, s12
	v_lshl_add_u32 v191, v191, 2, s12
	v_lshl_add_u32 v193, v193, 2, s12
	v_lshl_add_u32 v198, v198, 2, s12
	ds_read_b32 v196, v192 offset:512
	ds_read_b32 v200, v191 offset:640
	ds_read_b32 v197, v197 offset:512
	ds_read_b32 v201, v193 offset:640
	ds_read_b32 v202, v198 offset:512
	ds_read_b32 v204, v199 offset:640
	ds_read_b32 v203, v203 offset:512
	ds_read_b32 v205, v205 offset:640
	s_waitcnt lgkmcnt(8)
	v_pk_add_f32 v[192:193], v[146:147], v[194:195]
	s_waitcnt lgkmcnt(4)
	v_pk_add_f32 v[194:195], v[148:149], v[200:201]
	v_pk_add_f32 v[198:199], v[132:133], v[196:197]
	s_waitcnt lgkmcnt(1)
	v_pk_add_f32 v[200:201], v[134:135], v[202:203]
	v_add_u32_e32 v203, 17, v190
	s_waitcnt lgkmcnt(0)
; __device__ __forceinline__ void partialSM(f32x16& p0, f32x16& p1, float& m_reg, float& mn, float& alpha, float cadd) {
;   float pmax = p0[0];
; #pragma unroll
;   for (int r = 1; r < 16; ++r) pmax = fmaxf(pmax, p0[r]);
; #pragma unroll
;   for (int r = 0; r < 16; ++r) pmax = fmaxf(pmax, p1[r]);
;   { auto rr = __builtin_amdgcn_permlane32_swap(__float_as_uint(pmax), __float_as_uint(pmax), false, false);
;     pmax = fmaxf(__uint_as_float(rr[0]), __uint_as_float(rr[1])); }
;   pmax += cadd;
;   if (__builtin_expect(__all(pmax - m_reg <= THRL), 1)) { mn = m_reg; alpha = 1.f; }
;   else { mn = fmaxf(m_reg, pmax); alpha = __builtin_amdgcn_exp2f(m_reg - mn); m_reg = mn; }
; __device__ __forceinline__ void attn_pass_dv256(const bf16_t* __restrict__ Qb, const bf16_t* __restrict__ Kh, const bf16_t* __restrict__ Vh, int qpos0,
;                                                 LAS unsigned char* lds, f32x16 (&o)[8], float& l_out, int wave_) {
;     ...
;       if (dd <= -191 || dd >= 159) { cadd = (dd < 0) ? tbl[0] : tbl[256]; partialSM(p0, p1, m_reg, mn, al, cadd); }
;       else { add_bias(p0, p1, tbl, j * KVBLK - qme, hi); partialSM(p0, p1, m_reg, mn, al, 0.f); } }
	v_pk_add_f32 v[196:197], v[150:151], v[204:205]
	v_med3_i32 v204, v203, s50, v228
	v_med3_i32 v203, v203, s51, v229
	v_lshl_add_u32 v205, v203, 2, s12
	v_add_u32_e32 v203, 18, v190
	v_med3_i32 v206, v203, s50, v228
	v_med3_i32 v203, v203, s51, v229
	v_add_u32_e32 v191, 16, v190
	v_lshl_add_u32 v210, v203, 2, s12
	v_add_u32_e32 v203, 19, v190
	v_med3_i32 v202, v191, s50, v228
	v_lshl_add_u32 v208, v206, 2, s12
	v_med3_i32 v206, v203, s50, v228
	v_med3_i32 v203, v203, s51, v229
	v_lshl_add_u32 v202, v202, 2, s12
	v_med3_i32 v191, v191, s51, v229
	v_lshl_add_u32 v209, v206, 2, s12
	v_lshl_add_u32 v211, v203, 2, s12
	v_lshl_add_u32 v191, v191, 2, s12
	v_lshl_add_u32 v204, v204, 2, s12
	ds_read_b32 v202, v202 offset:512
	ds_read_b32 v206, v191 offset:640
	ds_read_b32 v203, v204 offset:512
	ds_read_b32 v207, v205 offset:640
	ds_read_b32 v208, v208 offset:512
	ds_read_b32 v209, v209 offset:512
	ds_read_b32 v211, v211 offset:640
	ds_read_b32 v210, v210 offset:640
	s_waitcnt lgkmcnt(5)
	v_pk_add_f32 v[204:205], v[136:137], v[202:203]
	s_waitcnt lgkmcnt(4)
	v_pk_add_f32 v[202:203], v[152:153], v[206:207]
	s_waitcnt lgkmcnt(2)
	v_pk_add_f32 v[206:207], v[138:139], v[208:209]
	v_add_u32_e32 v209, 25, v190
	v_med3_i32 v212, v209, s50, v228
	v_lshl_add_u32 v213, v212, 2, s12
	v_add_u32_e32 v212, 26, v190
	v_add_u32_e32 v191, 24, v190
	v_med3_i32 v214, v212, s50, v228
	v_med3_i32 v212, v212, s51, v229
	v_add_u32_e32 v190, 27, v190
	v_med3_i32 v208, v191, s50, v228
	v_med3_i32 v191, v191, s51, v229
	v_lshl_add_u32 v215, v212, 2, s12
	v_med3_i32 v212, v190, s50, v228
	v_med3_i32 v190, v190, s51, v229
	v_lshl_add_u32 v208, v208, 2, s12
	v_lshl_add_u32 v191, v191, 2, s12
	v_med3_i32 v209, v209, s51, v229
	v_lshl_add_u32 v223, v190, 2, s12
	v_lshl_add_u32 v209, v209, 2, s12
	v_lshl_add_u32 v214, v214, 2, s12
	v_lshl_add_u32 v221, v212, 2, s12
	ds_read_b32 v212, v208 offset:512
	ds_read_b32 v216, v191 offset:640
	ds_read_b32 v213, v213 offset:512
	ds_read_b32 v217, v209 offset:640
	ds_read_b32 v190, v214 offset:512
	ds_read_b32 v222, v215 offset:640
	ds_read_b32 v191, v221 offset:512
	ds_read_b32 v223, v223 offset:640
	s_waitcnt lgkmcnt(8)
	v_pk_add_f32 v[208:209], v[154:155], v[210:211]
	s_waitcnt lgkmcnt(4)
	v_pk_add_f32 v[210:211], v[156:157], v[216:217]
	v_pk_add_f32 v[214:215], v[140:141], v[212:213]
	s_waitcnt lgkmcnt(1)
	v_pk_add_f32 v[216:217], v[142:143], v[190:191]
	v_max_f32_e32 v190, v180, v181
	v_max3_f32 v190, v190, v182, v183
	v_max3_f32 v190, v190, v198, v199
	v_max3_f32 v190, v190, v200, v201
	v_max3_f32 v190, v190, v204, v205
	v_max3_f32 v190, v190, v206, v207
	v_max3_f32 v190, v190, v214, v215
	v_max3_f32 v190, v190, v216, v217
	v_max3_f32 v190, v190, v178, v179
	v_max3_f32 v190, v190, v192, v193
	v_max3_f32 v190, v190, v194, v195
	v_max3_f32 v190, v190, v196, v197
	v_max3_f32 v190, v190, v202, v203
	v_max3_f32 v190, v190, v208, v209
	s_waitcnt lgkmcnt(0)
	v_pk_add_f32 v[212:213], v[158:159], v[222:223]
	v_max3_f32 v190, v190, v210, v211
	v_max3_f32 v190, v190, v212, v213
	v_mov_b32_e32 v191, v190
	s_nop 1
	v_permlane32_swap_b32_e32 v190, v191
	v_max_f32_e32 v190, v190, v191
	v_add_f32_e32 v221, 0, v190
	v_sub_f32_e32 v190, v221, v249
	v_cmp_ge_f32_e32 vcc, s94, v190
	s_cmp_eq_u64 vcc, exec
	s_mov_b64 s[24:25], 0
	s_cselect_b64 s[12:13], -1, 0
.LBB0_376:
	s_andn2_b64 vcc, exec, s[24:25]
	v_mov_b32_e32 v251, 0
	s_cbranch_vccnz .LBB0_378
	s_cmp_lt_i32 s16, 0
	s_mov_b32 s12, 0x18c00
	s_cselect_b32 s12, 0x18800, s12
	s_add_i32 s12, s12, 0
	v_mov_b32_e32 v178, s12
	ds_read_b32 v251, v178
	s_nop 0
	v_max_f32_e32 v178, v128, v129
	v_max3_f32 v178, v178, v130, v131
	v_max3_f32 v178, v178, v132, v133
	v_max3_f32 v178, v178, v134, v135
	v_max3_f32 v178, v178, v136, v137
	v_max3_f32 v178, v178, v138, v139
	v_max3_f32 v178, v178, v140, v141
	v_max3_f32 v178, v178, v142, v143
	v_max3_f32 v178, v178, v144, v145
	v_max3_f32 v178, v178, v146, v147
	v_max3_f32 v178, v178, v148, v149
	v_max3_f32 v178, v178, v150, v151
	v_max3_f32 v178, v178, v152, v153
	v_max3_f32 v178, v178, v154, v155
	v_max3_f32 v178, v178, v156, v157
	v_max3_f32 v178, v178, v158, v159
	v_mov_b32_e32 v179, v178
	s_nop 1
	v_permlane32_swap_b32_e32 v178, v179
	v_max_f32_e32 v178, v178, v179
	s_waitcnt lgkmcnt(0)
	v_add_f32_e32 v221, v251, v178
	v_sub_f32_e32 v178, v221, v249
	v_cmp_ge_f32_e32 vcc, s94, v178
	s_cmp_eq_u64 vcc, exec
	s_cselect_b64 s[12:13], -1, 0
	s_cbranch_scc0 .Lslow_p1
	v_sub_f32_e32 v180, v251, v249
	v_add_f32_e32 v181, v180, v159
	v_add_f32_e32 v159, v180, v157
	v_add_f32_e32 v178, v180, v158
	v_add_f32_e32 v157, v180, v155
	v_add_f32_e32 v158, v180, v156
	v_add_f32_e32 v155, v180, v153
	v_add_f32_e32 v156, v180, v154
	v_add_f32_e32 v153, v180, v151
	v_add_f32_e32 v154, v180, v152
	v_add_f32_e32 v151, v180, v149
	v_add_f32_e32 v152, v180, v150
	v_add_f32_e32 v149, v180, v147
	v_add_f32_e32 v150, v180, v148
	v_add_f32_e32 v147, v180, v145
	v_add_f32_e32 v148, v180, v146
	v_add_f32_e32 v145, v180, v143
	v_add_f32_e32 v146, v180, v144
	v_add_f32_e32 v143, v180, v142
	v_add_f32_e32 v142, v180, v141
	v_add_f32_e32 v141, v180, v140
	v_add_f32_e32 v140, v180, v139
	v_add_f32_e32 v139, v180, v138
	v_add_f32_e32 v138, v180, v137
	v_add_f32_e32 v137, v180, v136
	v_add_f32_e32 v136, v180, v135
	v_add_f32_e32 v135, v180, v134
	v_add_f32_e32 v134, v180, v133
	v_add_f32_e32 v133, v180, v132
	v_add_f32_e32 v132, v180, v131
	v_add_f32_e32 v131, v180, v130
	v_add_f32_e32 v130, v180, v129
	v_add_f32_e32 v129, v180, v128
	v_mov_b32_e32 v128, v181
	v_exp_f32_e32 v129, v129
	v_exp_f32_e32 v130, v130
	v_exp_f32_e32 v131, v131
	v_mov_b32_e32 v144, 1.0
	s_branch .Ljoin_p1

; #define LAS __attribute__((address_space(3)))
; __device__ __forceinline__ int crow(int r, int hi) { return (r & 3) + 8 * (r >> 2) + 4 * hi; }
; __device__ __forceinline__ void add_bias(f32x16& p0, f32x16& p1, const LAS float* tbl, int kq, int hi) {
; #pragma unroll
;   for (int r = 0; r < 16; ++r) { const int rel = kq + crow(r, hi);
;     p0[r] += tbl[min(max(rel, -128), 128) + 128]; p1[r] += tbl[min(max(rel + 32, -128), 128) + 128]; }
; }
; __device__ __forceinline__ void attn_pass_dv256(const bf16_t* __restrict__ Qb, const bf16_t* __restrict__ Kh, const bf16_t* __restrict__ Vh, int qpos0,
;                                                 LAS unsigned char* lds, f32x16 (&o)[8], float& l_out, int wave_) {
;     ...
;     { const LAS unsigned char* Ks = K_lds + sl * SHM_K; p0 = f32x16{}; p1 = f32x16{};
; #pragma unroll
;       for (int d0 = 0; d0 < 8; ++d0) { const int cb = (d0 * 16 + hi * 8) * 2;
;         const bf16x8 b0 = *(const LAS bf16x8*)(Ks + KSWZ(r32, cb)), b1 = *(const LAS bf16x8*)(Ks + KSWZ(32 + r32, cb));
;         const bf16x8 q = d0 < 4 ? qr[d0 & 3] : *(const LAS bf16x8*)(qf + ((d0 - 4) * 64 + lane) * 16);
;         p0 = __builtin_amdgcn_mfma_f32_32x32x16_bf16(b0, q, p0, 0, 0, 0); p1 = __builtin_amdgcn_mfma_f32_32x32x16_bf16(b1, q, p1, 0, 0, 0); } }
;     { const int dd = j * KVBLK - qw0;
;       if (dd <= -191 || dd >= 159) { cadd = (dd < 0) ? tbl[0] : tbl[256]; partialSM(p0, p1, m_reg, mn, al, cadd); }
;       else { add_bias(p0, p1, tbl, j * KVBLK - qme, hi); partialSM(p0, p1, m_reg, mn, al, 0.f); } }
.LBB0_389:
	s_and_b32 s19, s17, 1
	s_lshl_b32 s18, s19, 14
	v_add_u32_e32 v182, s18, v237
	v_add_u32_e32 v132, v182, v239
	ds_read_b128 v[128:131], v132
	ds_read_b128 v[144:147], v132 offset:8192
	v_add_u32_e32 v183, v182, v240
	ds_read_b128 v[178:181], v183
	ds_read_b128 v[192:195], v183 offset:8192
	v_add_u32_e32 v183, v182, v241
	ds_read_b128 v[200:203], v183
	ds_read_b128 v[204:207], v183 offset:8192
	s_add_i32 s24, s30, s16
	s_add_i32 s6, s24, 0xffffff61
	s_mov_b64 s[8:9], -1
	s_cmp_gt_u32 s6, 0xfffffea2
	s_waitcnt lgkmcnt(5)
	v_mfma_f32_32x32x16_bf16 v[128:143], v[128:131], v[160:163], 0
	s_waitcnt lgkmcnt(4)
	v_mfma_f32_32x32x16_bf16 v[144:159], v[144:147], v[160:163], 0
	s_waitcnt lgkmcnt(3)
	v_mfma_f32_32x32x16_bf16 v[128:143], v[178:181], v[164:167], v[128:143]
	s_waitcnt lgkmcnt(2)
	v_mfma_f32_32x32x16_bf16 v[144:159], v[192:195], v[164:167], v[144:159]
	v_add_u32_e32 v183, v182, v242
	ds_read_b128 v[178:181], v183
	ds_read_b128 v[192:195], v183 offset:8192
	s_waitcnt lgkmcnt(3)
	v_mfma_f32_32x32x16_bf16 v[128:143], v[200:203], v[168:171], v[128:143]
	s_waitcnt lgkmcnt(2)
	v_mfma_f32_32x32x16_bf16 v[144:159], v[204:207], v[168:171], v[144:159]
	v_add_u32_e32 v183, v182, v243
	ds_read_b128 v[200:203], v183
	ds_read_b128 v[204:207], v183 offset:8192
	ds_read_b128 v[208:211], v234
	s_waitcnt lgkmcnt(4)
	v_mfma_f32_32x32x16_bf16 v[128:143], v[178:181], v[172:175], v[128:143]
	s_waitcnt lgkmcnt(3)
	v_mfma_f32_32x32x16_bf16 v[144:159], v[192:195], v[172:175], v[144:159]
	v_add_u32_e32 v183, v182, v244
	ds_read_b128 v[178:181], v183
	ds_read_b128 v[192:195], v183 offset:8192
	ds_read_b128 v[196:199], v234 offset:1024
	s_waitcnt lgkmcnt(3)
	v_mfma_f32_32x32x16_bf16 v[128:143], v[200:203], v[208:211], v[128:143]
	v_mfma_f32_32x32x16_bf16 v[144:159], v[204:207], v[208:211], v[144:159]
	v_add_u32_e32 v183, v182, v245
	ds_read_b128 v[200:203], v183
	ds_read_b128 v[204:207], v183 offset:8192
	ds_read_b128 v[208:211], v234 offset:2048
	s_waitcnt lgkmcnt(3)
	v_mfma_f32_32x32x16_bf16 v[128:143], v[178:181], v[196:199], v[128:143]
	v_mfma_f32_32x32x16_bf16 v[144:159], v[192:195], v[196:199], v[144:159]
	v_add_u32_e32 v182, v182, v246
	ds_read_b128 v[178:181], v182
	ds_read_b128 v[192:195], v182 offset:8192
	ds_read_b128 v[196:199], v234 offset:3072
	s_waitcnt lgkmcnt(3)
	v_mfma_f32_32x32x16_bf16 v[128:143], v[200:203], v[208:211], v[128:143]
	v_mfma_f32_32x32x16_bf16 v[144:159], v[204:207], v[208:211], v[144:159]
	s_waitcnt lgkmcnt(0)
	v_mfma_f32_32x32x16_bf16 v[128:143], v[178:181], v[196:199], v[128:143]
	v_mfma_f32_32x32x16_bf16 v[144:159], v[192:195], v[196:199], v[144:159]
	s_cbranch_scc0 .LBB0_391
	v_add_u32_e32 v210, s16, v248
	v_add_u32_e32 v182, 2, v210
	s_add_i32 s6, 0, 0x18800
	v_med3_i32 v183, v182, s50, v228
	v_med3_i32 v182, v182, s51, v229
	v_lshl_add_u32 v192, v182, 2, s6
	v_add_u32_e32 v182, 3, v210
	v_med3_i32 v178, v210, s50, v228
	v_med3_i32 v179, v210, s51, v229
	v_add_u32_e32 v180, 1, v210
	v_lshl_add_u32 v190, v183, 2, s6
	v_med3_i32 v183, v182, s50, v228
	v_med3_i32 v182, v182, s51, v229
	v_lshl_add_u32 v178, v178, 2, s6
	v_lshl_add_u32 v179, v179, 2, s6
	v_med3_i32 v181, v180, s50, v228
	v_med3_i32 v180, v180, s51, v229
	v_lshl_add_u32 v191, v183, 2, s6
	v_lshl_add_u32 v193, v182, 2, s6
	v_lshl_add_u32 v181, v181, 2, s6
	v_lshl_add_u32 v180, v180, 2, s6
	ds_read_b32 v178, v178 offset:512
	ds_read_b32 v182, v179 offset:640
	ds_read_b32 v179, v181 offset:512
	ds_read_b32 v183, v180 offset:640
	ds_read_b32 v190, v190 offset:512
	ds_read_b32 v191, v191 offset:512
	ds_read_b32 v193, v193 offset:640
	ds_read_b32 v192, v192 offset:640
	s_waitcnt lgkmcnt(5)
	v_pk_add_f32 v[180:181], v[128:129], v[178:179]
	s_waitcnt lgkmcnt(4)
	v_pk_add_f32 v[178:179], v[144:145], v[182:183]
	s_waitcnt lgkmcnt(2)
	v_pk_add_f32 v[182:183], v[130:131], v[190:191]
	v_add_u32_e32 v190, 8, v210
	v_med3_i32 v191, v190, s50, v228
	v_med3_i32 v190, v190, s51, v229
	v_lshl_add_u32 v194, v190, 2, s6
	v_add_u32_e32 v190, 9, v210
	v_med3_i32 v195, v190, s50, v228
	v_med3_i32 v190, v190, s51, v229
	v_lshl_add_u32 v196, v190, 2, s6
	v_add_u32_e32 v190, 10, v210
	v_med3_i32 v197, v190, s50, v228
	v_med3_i32 v190, v190, s51, v229
	v_lshl_add_u32 v198, v190, 2, s6
	v_add_u32_e32 v190, 11, v210
	v_lshl_add_u32 v191, v191, 2, s6
	v_lshl_add_u32 v195, v195, 2, s6
	v_lshl_add_u32 v197, v197, 2, s6
	v_med3_i32 v199, v190, s50, v228
	v_med3_i32 v190, v190, s51, v229
	v_lshl_add_u32 v199, v199, 2, s6
	v_lshl_add_u32 v200, v190, 2, s6
	ds_read_b32 v190, v191 offset:512
	ds_read_b32 v194, v194 offset:640
	ds_read_b32 v191, v195 offset:512
	ds_read_b32 v195, v196 offset:640
	ds_read_b32 v196, v197 offset:512
	ds_read_b32 v202, v198 offset:640
	ds_read_b32 v197, v199 offset:512
	ds_read_b32 v203, v200 offset:640
	s_waitcnt lgkmcnt(5)
	v_pk_add_f32 v[198:199], v[132:133], v[190:191]
	v_add_u32_e32 v190, 16, v210
	v_med3_i32 v191, v190, s50, v228
	v_med3_i32 v190, v190, s51, v229
	s_waitcnt lgkmcnt(1)
	v_pk_add_f32 v[200:201], v[134:135], v[196:197]
	s_waitcnt lgkmcnt(0)
; __device__ __forceinline__ void partialSM(f32x16& p0, f32x16& p1, float& m_reg, float& mn, float& alpha, float cadd) {
;   float pmax = p0[0];
; #pragma unroll
;   for (int r = 1; r < 16; ++r) pmax = fmaxf(pmax, p0[r]);
; #pragma unroll
;   for (int r = 0; r < 16; ++r) pmax = fmaxf(pmax, p1[r]);
;   { auto rr = __builtin_amdgcn_permlane32_swap(__float_as_uint(pmax), __float_as_uint(pmax), false, false);
;     pmax = fmaxf(__uint_as_float(rr[0]), __uint_as_float(rr[1])); }
;   pmax += cadd;
;   if (__builtin_expect(__all(pmax - m_reg <= THRL), 1)) { mn = m_reg; alpha = 1.f; }
;   else { mn = fmaxf(m_reg, pmax); alpha = __builtin_amdgcn_exp2f(m_reg - mn); m_reg = mn; }
; __device__ __forceinline__ void attn_pass_dv256(const bf16_t* __restrict__ Qb, const bf16_t* __restrict__ Kh, const bf16_t* __restrict__ Vh, int qpos0,
;                                                 LAS unsigned char* lds, f32x16 (&o)[8], float& l_out, int wave_) {
;     ...
;       if (dd <= -191 || dd >= 159) { cadd = (dd < 0) ? tbl[0] : tbl[256]; partialSM(p0, p1, m_reg, mn, al, cadd); }
;       else { add_bias(p0, p1, tbl, j * KVBLK - qme, hi); partialSM(p0, p1, m_reg, mn, al, 0.f); } }
	v_pk_add_f32 v[196:197], v[150:151], v[202:203]
	v_lshl_add_u32 v202, v190, 2, s6
	v_add_u32_e32 v190, 17, v210
	v_med3_i32 v203, v190, s50, v228
	v_med3_i32 v190, v190, s51, v229
	v_lshl_add_u32 v204, v190, 2, s6
	v_add_u32_e32 v190, 18, v210
	v_med3_i32 v205, v190, s50, v228
	v_med3_i32 v190, v190, s51, v229
	v_lshl_add_u32 v208, v190, 2, s6
	v_add_u32_e32 v190, 19, v210
	v_med3_i32 v206, v190, s50, v228
	v_med3_i32 v190, v190, s51, v229
	v_lshl_add_u32 v191, v191, 2, s6
	v_lshl_add_u32 v203, v203, 2, s6
	v_lshl_add_u32 v207, v206, 2, s6
	v_lshl_add_u32 v209, v190, 2, s6
	v_lshl_add_u32 v205, v205, 2, s6
	ds_read_b32 v190, v191 offset:512
	ds_read_b32 v202, v202 offset:640
	ds_read_b32 v191, v203 offset:512
	ds_read_b32 v203, v204 offset:640
	ds_read_b32 v206, v205 offset:512
	ds_read_b32 v207, v207 offset:512
	ds_read_b32 v209, v209 offset:640
	ds_read_b32 v208, v208 offset:640
	s_waitcnt lgkmcnt(5)
	v_pk_add_f32 v[204:205], v[136:137], v[190:191]
	v_add_u32_e32 v190, 24, v210
	v_med3_i32 v191, v190, s50, v228
	v_med3_i32 v190, v190, s51, v229
	v_lshl_add_u32 v211, v190, 2, s6
	v_add_u32_e32 v190, 25, v210
	v_med3_i32 v212, v190, s50, v228
	v_med3_i32 v190, v190, s51, v229
	v_lshl_add_u32 v213, v190, 2, s6
	v_add_u32_e32 v190, 26, v210
	v_med3_i32 v214, v190, s50, v228
	v_med3_i32 v190, v190, s51, v229
	v_lshl_add_u32 v215, v190, 2, s6
	v_add_u32_e32 v190, 27, v210
	v_lshl_add_u32 v191, v191, 2, s6
	v_lshl_add_u32 v212, v212, 2, s6
	v_med3_i32 v210, v190, s50, v228
	v_med3_i32 v190, v190, s51, v229
	v_lshl_add_u32 v214, v214, 2, s6
	v_lshl_add_u32 v216, v210, 2, s6
	v_lshl_add_u32 v217, v190, 2, s6
	ds_read_b32 v190, v191 offset:512
	ds_read_b32 v210, v211 offset:640
	ds_read_b32 v191, v212 offset:512
	ds_read_b32 v211, v213 offset:640
	ds_read_b32 v212, v214 offset:512
	ds_read_b32 v222, v215 offset:640
	ds_read_b32 v213, v216 offset:512
	ds_read_b32 v223, v217 offset:640
	s_waitcnt lgkmcnt(5)
	v_pk_add_f32 v[214:215], v[140:141], v[190:191]
	v_max_f32_e32 v190, v180, v181
	v_max3_f32 v190, v190, v182, v183
	v_max3_f32 v190, v190, v198, v199
	v_max3_f32 v190, v190, v200, v201
	v_pk_add_f32 v[206:207], v[138:139], v[206:207]
	v_max3_f32 v190, v190, v204, v205
	v_max3_f32 v190, v190, v206, v207
	s_waitcnt lgkmcnt(1)
	v_pk_add_f32 v[216:217], v[142:143], v[212:213]
	v_max3_f32 v190, v190, v214, v215
	v_max3_f32 v190, v190, v216, v217
	v_pk_add_f32 v[192:193], v[146:147], v[192:193]
	v_max3_f32 v190, v190, v178, v179
	v_pk_add_f32 v[194:195], v[148:149], v[194:195]
	v_max3_f32 v190, v190, v192, v193
	v_max3_f32 v190, v190, v194, v195
	v_pk_add_f32 v[202:203], v[152:153], v[202:203]
	v_max3_f32 v190, v190, v196, v197
	v_pk_add_f32 v[208:209], v[154:155], v[208:209]
	v_max3_f32 v190, v190, v202, v203
	v_pk_add_f32 v[210:211], v[156:157], v[210:211]
	v_max3_f32 v190, v190, v208, v209
	s_waitcnt lgkmcnt(0)
	v_pk_add_f32 v[212:213], v[158:159], v[222:223]
	v_max3_f32 v190, v190, v210, v211
	v_max3_f32 v190, v190, v212, v213
	v_mov_b32_e32 v191, v190
	s_nop 1
	v_permlane32_swap_b32_e32 v190, v191
	v_max_f32_e32 v190, v190, v191
	v_add_f32_e32 v221, 0, v190
	v_sub_f32_e32 v190, v221, v249
	v_cmp_ge_f32_e32 vcc, s94, v190
	s_cmp_eq_u64 vcc, exec
	s_mov_b64 s[8:9], 0
	s_cselect_b64 s[6:7], -1, 0
.LBB0_391:
	s_andn2_b64 vcc, exec, s[8:9]
	v_mov_b32_e32 v251, 0
	s_cbranch_vccnz .LBB0_393
	s_cmp_lt_i32 s24, 0
	s_mov_b32 s6, 0x18c00
	s_cselect_b32 s6, 0x18800, s6
	s_add_i32 s6, s6, 0
	v_mov_b32_e32 v178, s6
	ds_read_b32 v251, v178
	s_nop 0
	v_max_f32_e32 v178, v128, v129
	v_max3_f32 v178, v178, v130, v131
	v_max3_f32 v178, v178, v132, v133
	v_max3_f32 v178, v178, v134, v135
	v_max3_f32 v178, v178, v136, v137
	v_max3_f32 v178, v178, v138, v139
	v_max3_f32 v178, v178, v140, v141
	v_max3_f32 v178, v178, v142, v143
	v_max3_f32 v178, v178, v144, v145
	v_max3_f32 v178, v178, v146, v147
	v_max3_f32 v178, v178, v148, v149
	v_max3_f32 v178, v178, v150, v151
	v_max3_f32 v178, v178, v152, v153
	v_max3_f32 v178, v178, v154, v155
	v_max3_f32 v178, v178, v156, v157
	v_max3_f32 v178, v178, v158, v159
	v_mov_b32_e32 v179, v178
	s_nop 1
	v_permlane32_swap_b32_e32 v178, v179
	v_max_f32_e32 v178, v178, v179
	s_waitcnt lgkmcnt(0)
	v_add_f32_e32 v221, v251, v178
	v_sub_f32_e32 v178, v221, v249
	v_cmp_ge_f32_e32 vcc, s94, v178
	s_cmp_eq_u64 vcc, exec
	s_cselect_b64 s[6:7], -1, 0
	s_cbranch_scc0 .Lslow_p2
	v_sub_f32_e32 v180, v251, v249
	v_add_f32_e32 v181, v180, v159
	v_add_f32_e32 v159, v180, v157
	v_add_f32_e32 v178, v180, v158
	v_add_f32_e32 v157, v180, v155
	v_add_f32_e32 v158, v180, v156
	v_add_f32_e32 v155, v180, v153
	v_add_f32_e32 v156, v180, v154
	v_add_f32_e32 v153, v180, v151
	v_add_f32_e32 v154, v180, v152
	v_add_f32_e32 v151, v180, v149
	v_add_f32_e32 v152, v180, v150
	v_add_f32_e32 v149, v180, v147
	v_add_f32_e32 v150, v180, v148
	v_add_f32_e32 v147, v180, v145
	v_add_f32_e32 v148, v180, v146
	v_add_f32_e32 v145, v180, v143
	v_add_f32_e32 v146, v180, v144
	v_add_f32_e32 v143, v180, v142
	v_add_f32_e32 v142, v180, v141
	v_add_f32_e32 v141, v180, v140
	v_add_f32_e32 v140, v180, v139
	v_add_f32_e32 v139, v180, v138
	v_add_f32_e32 v138, v180, v137
	v_add_f32_e32 v137, v180, v136
	v_add_f32_e32 v136, v180, v135
	v_add_f32_e32 v135, v180, v134
	v_add_f32_e32 v134, v180, v133
	v_add_f32_e32 v133, v180, v132
	v_add_f32_e32 v132, v180, v131
	v_add_f32_e32 v131, v180, v130
	v_add_f32_e32 v130, v180, v129
	v_add_f32_e32 v129, v180, v128
	v_mov_b32_e32 v128, v181
	v_exp_f32_e32 v129, v129
	v_exp_f32_e32 v130, v130
	v_exp_f32_e32 v131, v131
	v_mov_b32_e32 v144, 1.0
	s_branch .Ljoin_p2

; #define LAS __attribute__((address_space(3)))
; __device__ __forceinline__ void finishSM(f32x16& p0, f32x16& p1, float alpha, float& l_reg, bf16x8& pa0, bf16x8& pa1, bf16x8& pa2, bf16x8& pa3) {
; #pragma unroll
;   for (int r = 0; r < 16; ++r) p1[r] = __builtin_amdgcn_exp2f(p1[r]);
;   float ps = 0;
; #pragma unroll
;   for (int r = 0; r < 16; ++r) ps += p0[r];
; #pragma unroll
;   for (int r = 0; r < 16; ++r) ps += p1[r];
;   { auto rr = __builtin_amdgcn_permlane32_swap(__float_as_uint(ps), __float_as_uint(ps), false, false);
;     ps = __uint_as_float(rr[0]) + __uint_as_float(rr[1]); }
;   l_reg = l_reg * alpha + ps;
;     ...
;   PK4(p0, 0, pa0); PK4(p0, 8, pa1); PK4(p1, 0, pa2); PK4(p1, 8, pa3);
; template <int MODE>
; __device__ __forceinline__ void qkt(f32x16& p0, f32x16& p1, const LAS unsigned char* Ks, const LAS unsigned char* Krs, const LAS unsigned char* qrf, const bf16x8* qr, int r32, int hi, int lane) {
;   p0 = f32x16{}; p1 = f32x16{};
; #pragma unroll
;   for (int d0 = 0; d0 < 8; ++d0) { const int cb = (d0 * 16 + hi * 8) * 2;
;     const bf16x8 b0 = *(const LAS bf16x8*)(Ks + KSWZ(r32, cb));
;     const bf16x8 b1 = *(const LAS bf16x8*)(Ks + KSWZ(32 + r32, cb));
;     p0 = __builtin_amdgcn_mfma_f32_32x32x16_bf16(b0, qr[d0], p0, 0, 0, 0);
;     p1 = __builtin_amdgcn_mfma_f32_32x32x16_bf16(b1, qr[d0], p1, 0, 0, 0); }
;   if constexpr (MODE == 0) {
; #pragma unroll
;     for (int d0 = 0; d0 < 4; ++d0) { const int ch = d0 * 2 + hi;
;       const bf16x8 b0 = *(const LAS bf16x8*)(Krs + KRSWZ(r32, ch));
;       const bf16x8 b1 = *(const LAS bf16x8*)(Krs + KRSWZ(32 + r32, ch));
;       const bf16x8 q = *(const LAS bf16x8*)(qrf + (d0 * 64 + lane) * 16);
;       p0 = __builtin_amdgcn_mfma_f32_32x32x16_bf16(b0, q, p0, 0, 0, 0);
;       p1 = __builtin_amdgcn_mfma_f32_32x32x16_bf16(b1, q, p1, 0, 0, 0); }
;   }
; }
.LBB0_939:
	ds_read_b128 v[64:67], v158 offset:49152
	ds_read_b128 v[68:71], v158 offset:57344
	s_waitcnt lgkmcnt(1)
	v_mfma_f32_32x32x16_bf16 v[80:95], v[64:67], v[100:103], 0
	s_waitcnt lgkmcnt(0)
	v_mfma_f32_32x32x16_bf16 v[64:79], v[68:71], v[100:103], 0
	ds_read_b128 v[206:209], v160 offset:49152
	ds_read_b128 v[210:213], v160 offset:57344
	v_exp_f32_e32 v181, v144
	v_exp_f32_e32 v190, v145
	v_add_f32_e32 v144, 0, v197
	v_add_u32_e32 v180, v175, v166
	v_add_u32_e32 v179, v175, v168
	v_add_u32_e32 v178, v175, v170
	v_add_u32_e32 v177, v175, v172
	v_add_f32_e32 v144, v198, v144
	s_waitcnt lgkmcnt(1)
	v_mfma_f32_32x32x16_bf16 v[80:95], v[206:209], v[116:119], v[80:95]
	s_waitcnt lgkmcnt(0)
	v_mfma_f32_32x32x16_bf16 v[64:79], v[210:213], v[116:119], v[64:79]
	ds_read_b128 v[206:209], v161 offset:49152
	ds_read_b128 v[210:213], v161 offset:57344
	v_exp_f32_e32 v191, v142
	v_exp_f32_e32 v205, v143
	v_add_f32_e32 v142, v199, v144
	v_add_f32_e32 v142, v201, v142
	v_add_f32_e32 v142, v202, v142
	v_add_f32_e32 v142, v204, v142
	v_add_f32_e32 v142, v200, v142
	v_add_f32_e32 v214, v203, v142
	s_waitcnt lgkmcnt(1)
	v_mfma_f32_32x32x16_bf16 v[80:95], v[206:209], v[124:127], v[80:95]
	s_waitcnt lgkmcnt(0)
	v_mfma_f32_32x32x16_bf16 v[64:79], v[210:213], v[124:127], v[64:79]
	ds_read_b128 v[142:145], v164 offset:49152
	ds_read_b128 v[206:209], v164 offset:57344
	v_exp_f32_e32 v210, v138
	v_exp_f32_e32 v211, v139
	v_add_f32_e32 v138, v193, v214
	v_add_f32_e32 v138, v194, v138
	v_add_f32_e32 v138, v195, v138
	v_add_f32_e32 v138, v196, v138
	v_add_f32_e32 v138, v182, v138
	v_add_f32_e32 v138, v183, v138
	s_waitcnt lgkmcnt(1)
	v_mfma_f32_32x32x16_bf16 v[80:95], v[142:145], v[120:123], v[80:95]
	s_waitcnt lgkmcnt(0)
	v_mfma_f32_32x32x16_bf16 v[64:79], v[206:209], v[120:123], v[64:79]
	ds_read_b128 v[142:145], v165 offset:49152
	ds_read_b128 v[206:209], v165 offset:57344
	v_exp_f32_e32 v212, v136
	v_exp_f32_e32 v213, v137
	v_add_f32_e32 v136, v184, v138
	v_add_f32_e32 v136, v192, v136
	v_add_f32_e32 v136, v181, v136
	v_add_f32_e32 v136, v190, v136
	v_add_f32_e32 v136, v191, v136
	v_add_f32_e32 v214, v205, v136
	s_waitcnt lgkmcnt(1)
	v_mfma_f32_32x32x16_bf16 v[80:95], v[142:145], v[112:115], v[80:95]
	s_waitcnt lgkmcnt(0)
	v_mfma_f32_32x32x16_bf16 v[64:79], v[206:209], v[112:115], v[64:79]
	ds_read_b128 v[136:139], v163 offset:49152
	ds_read_b128 v[142:145], v163 offset:57344
	v_exp_f32_e32 v206, v130
	v_exp_f32_e32 v207, v131
	v_add_f32_e32 v130, v210, v214
	v_add_f32_e32 v130, v211, v130
	v_add_f32_e32 v130, v212, v130
	v_add_f32_e32 v130, v213, v130
	v_add_f32_e32 v130, v206, v130
	v_add_f32_e32 v130, v207, v130
	s_waitcnt lgkmcnt(1)
	v_mfma_f32_32x32x16_bf16 v[80:95], v[136:139], v[108:111], v[80:95]
	s_waitcnt lgkmcnt(0)
	v_mfma_f32_32x32x16_bf16 v[64:79], v[142:145], v[108:111], v[64:79]
	ds_read_b128 v[136:139], v162 offset:49152
	ds_read_b128 v[142:145], v162 offset:57344
	v_exp_f32_e32 v208, v128
	v_exp_f32_e32 v209, v129
	v_cvt_pk_bf16_f32 v129, v199, v201
	v_cvt_pk_bf16_f32 v131, v200, v203
	v_add_f32_e32 v128, v208, v130
	v_add_f32_e32 v214, v209, v128
	v_cvt_pk_bf16_f32 v128, v197, v198
	v_cvt_pk_bf16_f32 v130, v202, v204
	s_waitcnt lgkmcnt(1)
	v_mfma_f32_32x32x16_bf16 v[80:95], v[136:139], v[104:107], v[80:95]
	s_waitcnt lgkmcnt(0)
	v_mfma_f32_32x32x16_bf16 v[64:79], v[142:145], v[104:107], v[64:79]
	ds_read_b128 v[136:139], v159 offset:49152
	ds_read_b128 v[142:145], v159 offset:57344
	v_exp_f32_e32 v215, v132
	v_exp_f32_e32 v216, v133
	v_permlane32_swap_b32_e32 v128, v130
	v_add_f32_e32 v132, v215, v214
	v_add_f32_e32 v202, v216, v132
	v_permlane32_swap_b32_e32 v129, v131
	v_cvt_pk_bf16_f32 v132, v193, v194
	v_cvt_pk_bf16_f32 v133, v195, v196
	s_waitcnt lgkmcnt(1)
	v_mfma_f32_32x32x16_bf16 v[80:95], v[136:139], v[96:99], v[80:95]
	s_waitcnt lgkmcnt(0)
	v_mfma_f32_32x32x16_bf16 v[64:79], v[142:145], v[96:99], v[64:79]
	ds_read_b128 v[136:139], v180
	ds_read_b128 v[194:197], v180 offset:4096
	ds_read_b128 v[198:201], v153
	v_exp_f32_e32 v144, v134
	v_exp_f32_e32 v145, v135
	v_cvt_pk_bf16_f32 v135, v184, v192
	v_add_f32_e32 v134, v144, v202
	v_add_f32_e32 v142, v145, v134
	v_mov_b32_e32 v143, v142
	s_nop 1
	v_permlane32_swap_b32_e32 v142, v143
	v_cvt_pk_bf16_f32 v134, v182, v183
	s_waitcnt lgkmcnt(0)
	v_mfma_f32_32x32x16_bf16 v[80:95], v[136:139], v[198:201], v[80:95]
	v_mfma_f32_32x32x16_bf16 v[64:79], v[194:197], v[198:201], v[64:79]
	ds_read_b128 v[192:195], v179
	ds_read_b128 v[196:199], v179 offset:4096
	ds_read_b128 v[200:203], v153 offset:1024
	v_permlane32_swap_b32_e32 v132, v134
	v_permlane32_swap_b32_e32 v133, v135
	v_cvt_pk_bf16_f32 v136, v181, v190
	v_cvt_pk_bf16_f32 v137, v191, v205
	v_cvt_pk_bf16_f32 v138, v210, v211
	v_cvt_pk_bf16_f32 v139, v212, v213
	s_waitcnt lgkmcnt(0)
	v_mfma_f32_32x32x16_bf16 v[80:95], v[192:195], v[200:203], v[80:95]
	v_mfma_f32_32x32x16_bf16 v[64:79], v[196:199], v[200:203], v[64:79]
	ds_read_b128 v[192:195], v178
	ds_read_b128 v[196:199], v178 offset:4096
	ds_read_b128 v[200:203], v153 offset:2048
	v_permlane32_swap_b32_e32 v136, v138
	v_permlane32_swap_b32_e32 v137, v139
	v_cvt_pk_bf16_f32 v204, v206, v207
	v_cvt_pk_bf16_f32 v205, v208, v209
	v_cvt_pk_bf16_f32 v206, v215, v216
	v_cvt_pk_bf16_f32 v207, v144, v145
	s_waitcnt lgkmcnt(0)
	v_mfma_f32_32x32x16_bf16 v[80:95], v[192:195], v[200:203], v[80:95]
	v_mfma_f32_32x32x16_bf16 v[64:79], v[196:199], v[200:203], v[64:79]
	ds_read_b128 v[192:195], v177
	ds_read_b128 v[200:203], v177 offset:4096
	ds_read_b128 v[196:199], v153 offset:3072
	v_permlane32_swap_b32_e32 v204, v206
	v_permlane32_swap_b32_e32 v205, v207
	s_waitcnt lgkmcnt(0)
; #define SBAR() __builtin_amdgcn_sched_barrier(0)
; template <int OFF> __device__ __forceinline__ s16x4 tr_read(unsigned vb) { s16x4 r; asm volatile("ds_read_b64_tr_b16 %0, %1 offset:%2" : "=&v"(r) : "v"(vb), "i"(OFF) : "memory"); return r; }
; #define BARL() asm volatile("s_waitcnt lgkmcnt(0)\n\ts_barrier" ::: "memory")
; template <int D0> __device__ __forceinline__ void pv_one(f32x16& od, unsigned vb, bf16x8 pa0, bf16x8 pa1, bf16x8 pa2, bf16x8 pa3) {
;   const s16x4 l0 = tr_read<v_rd_off(D0, 0, 0)>(vb), h0 = tr_read<v_rd_off(D0, 0, 1)>(vb), l1 = tr_read<v_rd_off(D0, 1, 0)>(vb), h1 = tr_read<v_rd_off(D0, 1, 1)>(vb);
;   const s16x4 l2 = tr_read<v_rd_off(D0, 2, 0)>(vb), h2 = tr_read<v_rd_off(D0, 2, 1)>(vb), l3 = tr_read<v_rd_off(D0, 3, 0)>(vb), h3 = tr_read<v_rd_off(D0, 3, 1)>(vb);
;   asm volatile("s_waitcnt lgkmcnt(0)" ::: "memory"); SBAR();
;     ...
;   od = __builtin_amdgcn_mfma_f32_32x32x16_bf16(pa0, PK(l0, h0), od, 0, 0, 0);
;   od = __builtin_amdgcn_mfma_f32_32x32x16_bf16(pa1, PK(l1, h1), od, 0, 0, 0);
;   od = __builtin_amdgcn_mfma_f32_32x32x16_bf16(pa2, PK(l2, h2), od, 0, 0, 0);
;   od = __builtin_amdgcn_mfma_f32_32x32x16_bf16(pa3, PK(l3, h3), od, 0, 0, 0);
;     ...
; }
; __device__ __forceinline__ void pv_d0(f32x16* o, unsigned vb, bf16x8 pa0, bf16x8 pa1, bf16x8 pa2, bf16x8 pa3) {
;   pv_one<0>(o[0], vb, pa0, pa1, pa2, pa3); pv_one<1>(o[1], vb, pa0, pa1, pa2, pa3); pv_one<2>(o[2], vb, pa0, pa1, pa2, pa3); pv_one<3>(o[3], vb, pa0, pa1, pa2, pa3);
; __device__ __forceinline__ void partialSM(f32x16& p0, f32x16& p1, float& m_reg, float& mn, float& alpha, float cadd) {
;   float pmax = p0[0];
; #pragma unroll
;   for (int r = 1; r < 16; ++r) pmax = fmaxf(pmax, p0[r]);
; #pragma unroll
;   for (int r = 0; r < 16; ++r) pmax = fmaxf(pmax, p1[r]);
;   { auto rr = __builtin_amdgcn_permlane32_swap(__float_as_uint(pmax), __float_as_uint(pmax), false, false);
;     pmax = fmaxf(__uint_as_float(rr[0]), __uint_as_float(rr[1])); }
;   pmax += cadd;
;   if (__builtin_expect(__all(pmax - m_reg <= THRL), 1)) { mn = m_reg; alpha = 1.f; }
;   else { mn = fmaxf(m_reg, pmax); alpha = __builtin_amdgcn_exp2f(m_reg - mn); m_reg = mn; }
; template <int MODE> ...
;     ...
;     pv_d0(o, vb0, pa0, pa1, pa2, pa3); BIAS(pB0, pB1, j * KVBLK, cadd); partialSM(pB0, pB1, m_reg, mnB, alB, cadd);
;     BARL();
;     DMA_K(j + 2, 1); DMA_V(j + 1, 0);
;     WAITV();
;     RESC(alB); BARL();
	v_mfma_f32_32x32x16_bf16 v[80:95], v[192:195], v[196:199], v[80:95]
	v_mfma_f32_32x32x16_bf16 v[64:79], v[200:203], v[196:199], v[64:79]
	ds_read_b64_tr_b16 v[192:193], v152 offset:0
	ds_read_b64_tr_b16 v[194:195], v152 offset:0x800
	ds_read_b64_tr_b16 v[196:197], v152 offset:0x1000
	ds_read_b64_tr_b16 v[198:199], v152 offset:0x1800
	ds_read_b64_tr_b16 v[200:201], v152 offset:0x2000
	ds_read_b64_tr_b16 v[202:203], v152 offset:0x2800
	ds_read_b64_tr_b16 v[208:209], v152 offset:0x3000
	ds_read_b64_tr_b16 v[210:211], v152 offset:0x3800
	s_waitcnt lgkmcnt(0)
	s_nop 0
	v_mfma_f32_32x32x16_bf16 v[0:15], v[128:131], v[192:195], v[0:15]
	ds_read_b64_tr_b16 v[192:193], v152 offset:0x200
	ds_read_b64_tr_b16 v[194:195], v152 offset:0xa00
	v_mfma_f32_32x32x16_bf16 v[0:15], v[132:135], v[196:199], v[0:15]
	ds_read_b64_tr_b16 v[196:197], v152 offset:0x1200
	ds_read_b64_tr_b16 v[198:199], v152 offset:0x1a00
	v_mfma_f32_32x32x16_bf16 v[0:15], v[136:139], v[200:203], v[0:15]
	ds_read_b64_tr_b16 v[200:201], v152 offset:0x2200
	ds_read_b64_tr_b16 v[202:203], v152 offset:0x2a00
	v_mfma_f32_32x32x16_bf16 v[0:15], v[204:207], v[208:211], v[0:15]
	ds_read_b64_tr_b16 v[208:209], v152 offset:0x3200
	ds_read_b64_tr_b16 v[210:211], v152 offset:0x3a00
	s_waitcnt lgkmcnt(0)
	v_mfma_f32_32x32x16_bf16 v[48:63], v[128:131], v[192:195], v[48:63]
	ds_read_b64_tr_b16 v[192:193], v152 offset:0x400
	ds_read_b64_tr_b16 v[194:195], v152 offset:0xc00
	v_mfma_f32_32x32x16_bf16 v[48:63], v[132:135], v[196:199], v[48:63]
	ds_read_b64_tr_b16 v[196:197], v152 offset:0x1400
	ds_read_b64_tr_b16 v[198:199], v152 offset:0x1c00
	v_mfma_f32_32x32x16_bf16 v[48:63], v[136:139], v[200:203], v[48:63]
	ds_read_b64_tr_b16 v[200:201], v152 offset:0x2400
	ds_read_b64_tr_b16 v[202:203], v152 offset:0x2c00
	v_mfma_f32_32x32x16_bf16 v[48:63], v[204:207], v[208:211], v[48:63]
	ds_read_b64_tr_b16 v[208:209], v152 offset:0x3400
	ds_read_b64_tr_b16 v[210:211], v152 offset:0x3c00
	s_waitcnt lgkmcnt(0)
	v_mfma_f32_32x32x16_bf16 v[32:47], v[128:131], v[192:195], v[32:47]
	ds_read_b64_tr_b16 v[192:193], v152 offset:0x600
	ds_read_b64_tr_b16 v[194:195], v152 offset:0xe00
	v_mfma_f32_32x32x16_bf16 v[32:47], v[132:135], v[196:199], v[32:47]
	ds_read_b64_tr_b16 v[196:197], v152 offset:0x1600
	ds_read_b64_tr_b16 v[198:199], v152 offset:0x1e00
	v_mfma_f32_32x32x16_bf16 v[32:47], v[136:139], v[200:203], v[32:47]
	ds_read_b64_tr_b16 v[200:201], v152 offset:0x2600
	ds_read_b64_tr_b16 v[202:203], v152 offset:0x2e00
	v_mfma_f32_32x32x16_bf16 v[32:47], v[204:207], v[208:211], v[32:47]
	ds_read_b64_tr_b16 v[208:209], v152 offset:0x3600
	ds_read_b64_tr_b16 v[210:211], v152 offset:0x3e00
	s_waitcnt lgkmcnt(0)
	v_mfma_f32_32x32x16_bf16 v[16:31], v[128:131], v[192:195], v[16:31]
	v_max_f32_e32 v128, v80, v81
	v_max3_f32 v128, v128, v82, v83
	v_max3_f32 v128, v128, v84, v85
	v_max3_f32 v128, v128, v86, v87
	v_max3_f32 v128, v128, v88, v89
	v_max3_f32 v128, v128, v90, v91
	v_max3_f32 v128, v128, v92, v93
	v_max3_f32 v128, v128, v94, v95
	v_max3_f32 v128, v128, v64, v65
	v_max3_f32 v128, v128, v66, v67
	v_max3_f32 v128, v128, v68, v69
	v_max3_f32 v128, v128, v70, v71
	v_max3_f32 v128, v128, v72, v73
	v_max3_f32 v128, v128, v74, v75
	v_max3_f32 v128, v128, v76, v77
	v_mfma_f32_32x32x16_bf16 v[16:31], v[132:135], v[196:199], v[16:31]
	v_max3_f32 v128, v128, v78, v79
	v_mov_b32_e32 v129, v128
	s_nop 1
	v_permlane32_swap_b32_e32 v128, v129
	v_max_f32_e32 v128, v128, v129
	v_sub_f32_e32 v129, v128, v174
	v_cmp_ge_f32_e32 vcc, s94, v129
	v_mfma_f32_32x32x16_bf16 v[16:31], v[136:139], v[200:203], v[16:31]
	s_cmp_eq_u64 vcc, exec
	s_cselect_b64 s[40:41], -1, 0
	s_add_u32 s27, s19, s18
	s_addc_u32 s30, s21, 0
	s_add_u32 s12, s27, 0x294c0000
	s_waitcnt lgkmcnt(0)
	s_barrier
	s_addc_u32 s13, s30, 0
	s_mov_b32 m0, s14
	s_nop 0
	global_load_lds_dwordx4 v155, s[12:13]
	s_add_u32 s12, s27, 0x294e0000
	s_addc_u32 s13, s30, 0
	s_mov_b32 m0, s15
	s_nop 0
	global_load_lds_dwordx4 v155, s[12:13]
	v_max_f32_e32 v129, v174, v174
	s_add_u32 s27, s24, s18
	v_mfma_f32_32x32x16_bf16 v[16:31], v[204:207], v[208:211], v[16:31]
	v_max_f32_e32 v128, v129, v128
	v_readlane_b32 s13, v253, 48
	s_mov_b32 m0, s13
	s_nop 0
	global_load_lds_dwordx4 v157, s[10:11]
	s_addc_u32 s30, s25, 0
	v_sub_f32_e32 v129, v174, v128
	s_add_u32 s12, s27, 0x31480000
	v_exp_f32_e32 v129, v129
	s_addc_u32 s13, s30, 0
	s_mov_b32 m0, s76
	s_nop 0
	global_load_lds_dwordx4 v156, s[12:13]
	s_add_u32 s12, s27, 0x314a0000
	s_addc_u32 s13, s30, 0
	s_mov_b32 m0, s89
	s_nop 0
	global_load_lds_dwordx4 v156, s[12:13]
	s_waitcnt vmcnt(5)
	v_cndmask_b32_e64 v144, v129, 1.0, s[40:41]
	v_cmp_gt_f32_e32 vcc, 1.0, v144
	s_cbranch_vccz .LBB0_943
	s_and_saveexec_b64 s[12:13], s[38:39]
	ds_write_b32 v154, v144
	s_or_b64 exec, exec, s[12:13]
	v_readlane_b32 s12, v253, 45
	s_waitcnt lgkmcnt(0)
	s_nop 1
	v_add_u32_e32 v129, s12, v140
	v_readlane_b32 s12, v253, 46
	s_nop 1
	v_add_u32_e32 v134, s12, v140
	v_readlane_b32 s12, v253, 44
	ds_read_b128 v[130:133], v129
	ds_read_b128 v[134:137], v134
	v_add_u32_e32 v129, s12, v140
	v_readlane_b32 s12, v253, 43
	ds_read_b128 v[192:195], v129
	s_waitcnt lgkmcnt(2)
	v_pk_mul_f32 v[8:9], v[8:9], v[130:131]
	v_add_u32_e32 v129, s12, v140
	ds_read_b128 v[196:199], v129
	s_waitcnt lgkmcnt(2)
	v_pk_mul_f32 v[12:13], v[12:13], v[134:135]
	s_waitcnt lgkmcnt(1)
	v_pk_mul_f32 v[4:5], v[4:5], v[192:193]
	v_pk_mul_f32 v[14:15], v[14:15], v[136:137]
	v_pk_mul_f32 v[10:11], v[10:11], v[132:133]
	v_pk_mul_f32 v[6:7], v[6:7], v[194:195]
	s_waitcnt lgkmcnt(0)
	v_pk_mul_f32 v[2:3], v[2:3], v[198:199]
	v_pk_mul_f32 v[0:1], v[0:1], v[196:197]
	v_pk_mul_f32 v[60:61], v[134:135], v[60:61]
	v_pk_mul_f32 v[56:57], v[130:131], v[56:57]
	v_pk_mul_f32 v[52:53], v[192:193], v[52:53]
	v_pk_mul_f32 v[62:63], v[136:137], v[62:63]
	v_pk_mul_f32 v[58:59], v[132:133], v[58:59]
	v_pk_mul_f32 v[54:55], v[194:195], v[54:55]
	v_pk_mul_f32 v[50:51], v[198:199], v[50:51]
	v_pk_mul_f32 v[48:49], v[196:197], v[48:49]
	v_pk_mul_f32 v[44:45], v[134:135], v[44:45]
	v_pk_mul_f32 v[40:41], v[130:131], v[40:41]
	v_pk_mul_f32 v[36:37], v[192:193], v[36:37]
	v_pk_mul_f32 v[46:47], v[136:137], v[46:47]
	v_pk_mul_f32 v[42:43], v[132:133], v[42:43]
	v_pk_mul_f32 v[38:39], v[194:195], v[38:39]
	v_pk_mul_f32 v[34:35], v[198:199], v[34:35]
	v_pk_mul_f32 v[32:33], v[196:197], v[32:33]
	v_pk_mul_f32 v[28:29], v[134:135], v[28:29]
	v_pk_mul_f32 v[24:25], v[130:131], v[24:25]
	v_pk_mul_f32 v[20:21], v[192:193], v[20:21]
	v_pk_mul_f32 v[30:31], v[136:137], v[30:31]
	v_pk_mul_f32 v[26:27], v[132:133], v[26:27]
	v_pk_mul_f32 v[22:23], v[194:195], v[22:23]
	v_pk_mul_f32 v[18:19], v[198:199], v[18:19]
	v_pk_mul_f32 v[16:17], v[196:197], v[16:17]
; #define LAS __attribute__((address_space(3)))
; __device__ __forceinline__ void partialSM(f32x16& p0, f32x16& p1, float& m_reg, float& mn, float& alpha, float cadd) {
;     ...
;   const float off = cadd - mn;
; #pragma unroll
;   for (int r = 0; r < 16; ++r) p0[r] += off;
; #pragma unroll
;   for (int r = 0; r < 16; ++r) p1[r] += off;
; #pragma unroll
;   for (int r = 0; r < 16; ++r) p0[r] = __builtin_amdgcn_exp2f(p0[r]);
; }
; __device__ __forceinline__ void finishSM(f32x16& p0, f32x16& p1, float alpha, float& l_reg, bf16x8& pa0, bf16x8& pa1, bf16x8& pa2, bf16x8& pa3) {
; #pragma unroll
;   for (int r = 0; r < 16; ++r) p1[r] = __builtin_amdgcn_exp2f(p1[r]);
;   float ps = 0;
; #pragma unroll
;   for (int r = 0; r < 16; ++r) ps += p0[r];
; #pragma unroll
;   for (int r = 0; r < 16; ++r) ps += p1[r];
;   { auto rr = __builtin_amdgcn_permlane32_swap(__float_as_uint(ps), __float_as_uint(ps), false, false);
;     ps = __uint_as_float(rr[0]) + __uint_as_float(rr[1]); }
;   l_reg = l_reg * alpha + ps;
;     ...
;   PK4(p0, 0, pa0); PK4(p0, 8, pa1); PK4(p1, 0, pa2); PK4(p1, 8, pa3);
; template <int MODE>
; __device__ __forceinline__ void qkt(f32x16& p0, f32x16& p1, const LAS unsigned char* Ks, const LAS unsigned char* Krs, const LAS unsigned char* qrf, const bf16x8* qr, int r32, int hi, int lane) {
;   p0 = f32x16{}; p1 = f32x16{};
; #pragma unroll
;   for (int d0 = 0; d0 < 8; ++d0) { const int cb = (d0 * 16 + hi * 8) * 2;
;     const bf16x8 b0 = *(const LAS bf16x8*)(Ks + KSWZ(r32, cb));
;     const bf16x8 b1 = *(const LAS bf16x8*)(Ks + KSWZ(32 + r32, cb));
;     p0 = __builtin_amdgcn_mfma_f32_32x32x16_bf16(b0, qr[d0], p0, 0, 0, 0);
;     p1 = __builtin_amdgcn_mfma_f32_32x32x16_bf16(b1, qr[d0], p1, 0, 0, 0); }
;   if constexpr (MODE == 0) {
; #pragma unroll
;     for (int d0 = 0; d0 < 4; ++d0) { const int ch = d0 * 2 + hi;
;       const bf16x8 b0 = *(const LAS bf16x8*)(Krs + KRSWZ(r32, ch));
;       const bf16x8 b1 = *(const LAS bf16x8*)(Krs + KRSWZ(32 + r32, ch));
;       const bf16x8 q = *(const LAS bf16x8*)(qrf + (d0 * 64 + lane) * 16);
;       p0 = __builtin_amdgcn_mfma_f32_32x32x16_bf16(b0, q, p0, 0, 0, 0);
;       p1 = __builtin_amdgcn_mfma_f32_32x32x16_bf16(b1, q, p1, 0, 0, 0); }
;   }
; }
.LBB0_943:
	s_waitcnt lgkmcnt(0)
	s_barrier
	v_cndmask_b32_e64 v145, v128, v174, s[40:41]
	s_add_i32 s26, s26, 2
	v_add_f32_e64 v80, v80, -v145
	v_add_f32_e64 v81, v81, -v145
	v_add_f32_e64 v82, v82, -v145
	v_add_f32_e64 v83, v83, -v145
	v_add_f32_e64 v84, v84, -v145
	v_add_f32_e64 v85, v85, -v145
	v_add_f32_e64 v86, v86, -v145
	v_add_f32_e64 v87, v87, -v145
	v_add_f32_e64 v88, v88, -v145
	v_add_f32_e64 v89, v89, -v145
	v_add_f32_e64 v90, v90, -v145
	v_add_f32_e64 v91, v91, -v145
	v_add_f32_e64 v92, v92, -v145
	v_add_f32_e64 v93, v93, -v145
	v_add_f32_e64 v94, v94, -v145
	v_add_f32_e64 v95, v95, -v145
	v_add_f32_e64 v174, v68, -v145
	v_add_f32_e64 v181, v69, -v145
	v_add_f32_e64 v182, v70, -v145
	v_add_f32_e64 v136, v64, -v145
	v_add_f32_e64 v137, v65, -v145
	v_add_f32_e64 v138, v66, -v145
	v_add_f32_e64 v139, v67, -v145
	v_add_f32_e64 v183, v71, -v145
	v_add_f32_e64 v184, v72, -v145
	v_add_f32_e64 v190, v73, -v145
	v_add_f32_e64 v191, v74, -v145
	v_add_f32_e64 v196, v75, -v145
	v_add_f32_e64 v197, v76, -v145
	v_add_f32_e64 v198, v77, -v145
	v_add_f32_e64 v204, v78, -v145
	v_add_f32_e64 v205, v79, -v145
	v_exp_f32_e32 v192, v80
	v_exp_f32_e32 v193, v81
	v_exp_f32_e32 v194, v82
	v_exp_f32_e32 v195, v83
	v_exp_f32_e32 v199, v84
	v_exp_f32_e32 v200, v85
	v_exp_f32_e32 v201, v86
	v_exp_f32_e32 v202, v87
	v_exp_f32_e32 v203, v88
	v_exp_f32_e32 v206, v89
	v_exp_f32_e32 v207, v90
	v_exp_f32_e32 v208, v91
	v_exp_f32_e32 v209, v92
	v_exp_f32_e32 v210, v93
	v_exp_f32_e32 v211, v94
	v_exp_f32_e32 v212, v95
	ds_read_b128 v[64:67], v158 offset:32768
	ds_read_b128 v[68:71], v158 offset:40960
	s_waitcnt lgkmcnt(1)
	v_mfma_f32_32x32x16_bf16 v[80:95], v[64:67], v[100:103], 0
	s_waitcnt lgkmcnt(0)
	v_mfma_f32_32x32x16_bf16 v[64:79], v[68:71], v[100:103], 0
	ds_read_b128 v[128:131], v160 offset:32768
	ds_read_b128 v[132:135], v160 offset:40960
	v_exp_f32_e32 v213, v136
	v_exp_f32_e32 v214, v137
	v_add_f32_e32 v136, 0, v192
	v_add_f32_e32 v136, v193, v136
	v_add_f32_e32 v136, v194, v136
	v_add_f32_e32 v136, v195, v136
	v_add_f32_e32 v136, v199, v136
	v_add_f32_e32 v136, v200, v136
	s_waitcnt lgkmcnt(1)
	v_mfma_f32_32x32x16_bf16 v[80:95], v[128:131], v[116:119], v[80:95]
	s_waitcnt lgkmcnt(0)
	v_mfma_f32_32x32x16_bf16 v[64:79], v[132:135], v[116:119], v[64:79]
	ds_read_b128 v[128:131], v161 offset:32768
	ds_read_b128 v[132:135], v161 offset:40960
	v_exp_f32_e32 v215, v138
	v_exp_f32_e32 v216, v139
	v_add_f32_e32 v136, v201, v136
	v_add_f32_e32 v136, v202, v136
	v_add_f32_e32 v136, v203, v136
	v_add_f32_e32 v136, v206, v136
	v_add_f32_e32 v136, v207, v136
	v_add_f32_e32 v136, v208, v136
	s_waitcnt lgkmcnt(1)
	v_mfma_f32_32x32x16_bf16 v[80:95], v[128:131], v[124:127], v[80:95]
	s_waitcnt lgkmcnt(0)
	v_mfma_f32_32x32x16_bf16 v[64:79], v[132:135], v[124:127], v[64:79]
	ds_read_b128 v[128:131], v164 offset:32768
	ds_read_b128 v[132:135], v164 offset:40960
	v_exp_f32_e32 v217, v174
	v_exp_f32_e32 v181, v181
	v_add_f32_e32 v136, v209, v136
	v_add_f32_e32 v136, v210, v136
	v_add_f32_e32 v136, v211, v136
	v_add_f32_e32 v136, v212, v136
	v_add_f32_e32 v136, v213, v136
	v_add_f32_e32 v136, v214, v136
	s_waitcnt lgkmcnt(1)
	v_mfma_f32_32x32x16_bf16 v[80:95], v[128:131], v[120:123], v[80:95]
	s_waitcnt lgkmcnt(0)
	v_mfma_f32_32x32x16_bf16 v[64:79], v[132:135], v[120:123], v[64:79]
	ds_read_b128 v[128:131], v165 offset:32768
	ds_read_b128 v[132:135], v165 offset:40960
	v_exp_f32_e32 v218, v182
	v_exp_f32_e32 v183, v183
	v_add_f32_e32 v136, v215, v136
	v_add_f32_e32 v136, v216, v136
	v_add_f32_e32 v136, v217, v136
	v_add_f32_e32 v136, v181, v136
	v_add_f32_e32 v136, v218, v136
	v_add_f32_e32 v174, v183, v136
	s_waitcnt lgkmcnt(1)
	v_mfma_f32_32x32x16_bf16 v[80:95], v[128:131], v[112:115], v[80:95]
	s_waitcnt lgkmcnt(0)
	v_mfma_f32_32x32x16_bf16 v[64:79], v[132:135], v[112:115], v[64:79]
	ds_read_b128 v[132:135], v163 offset:32768
	ds_read_b128 v[136:139], v163 offset:40960
	v_exp_f32_e32 v184, v184
	v_exp_f32_e32 v190, v190
	v_cvt_pk_bf16_f32 v129, v194, v195
	v_cvt_pk_bf16_f32 v130, v199, v200
	v_add_f32_e32 v128, v184, v174
	v_add_f32_e32 v174, v190, v128
	v_cvt_pk_bf16_f32 v128, v192, v193
	v_cvt_pk_bf16_f32 v131, v201, v202
	s_waitcnt lgkmcnt(1)
	v_mfma_f32_32x32x16_bf16 v[80:95], v[132:135], v[108:111], v[80:95]
	s_waitcnt lgkmcnt(0)
	v_mfma_f32_32x32x16_bf16 v[64:79], v[136:139], v[108:111], v[64:79]
	ds_read_b128 v[134:137], v162 offset:32768
	ds_read_b128 v[192:195], v162 offset:40960
	v_exp_f32_e32 v191, v191
	v_exp_f32_e32 v219, v196
	v_permlane32_swap_b32_e32 v128, v130
	v_add_f32_e32 v132, v191, v174
	v_add_f32_e32 v174, v219, v132
	v_permlane32_swap_b32_e32 v129, v131
	v_cvt_pk_bf16_f32 v132, v203, v206
	v_cvt_pk_bf16_f32 v133, v207, v208
	s_waitcnt lgkmcnt(1)
	v_mfma_f32_32x32x16_bf16 v[80:95], v[134:137], v[104:107], v[80:95]
	s_waitcnt lgkmcnt(0)
	v_mfma_f32_32x32x16_bf16 v[64:79], v[192:195], v[104:107], v[64:79]
	ds_read_b128 v[136:139], v159 offset:32768
	ds_read_b128 v[192:195], v159 offset:40960
	v_exp_f32_e32 v206, v197
	v_exp_f32_e32 v207, v198
	v_cvt_pk_bf16_f32 v135, v211, v212
	s_nop 1
	v_permlane32_swap_b32_e32 v133, v135
	v_add_f32_e32 v134, v206, v174
	v_add_f32_e32 v174, v207, v134
	v_cvt_pk_bf16_f32 v134, v209, v210
	s_nop 1
	v_permlane32_swap_b32_e32 v132, v134
	s_waitcnt lgkmcnt(1)
	v_mfma_f32_32x32x16_bf16 v[80:95], v[136:139], v[96:99], v[80:95]
	s_waitcnt lgkmcnt(0)
	v_mfma_f32_32x32x16_bf16 v[64:79], v[192:195], v[96:99], v[64:79]
	ds_read_b128 v[192:195], v167
	ds_read_b128 v[196:199], v167 offset:4096
	ds_read_b128 v[200:203], v153
	v_exp_f32_e32 v208, v204
	v_exp_f32_e32 v209, v205
	v_cvt_pk_bf16_f32 v137, v215, v216
	v_add_f32_e32 v136, v208, v174
	v_add_f32_e32 v174, v209, v136
	v_mov_b32_e32 v182, v174
	s_nop 1
	v_permlane32_swap_b32_e32 v174, v182
	v_cvt_pk_bf16_f32 v136, v213, v214
	s_waitcnt lgkmcnt(0)
; #define SBAR() __builtin_amdgcn_sched_barrier(0)
; template <int OFF> __device__ __forceinline__ s16x4 tr_read(unsigned vb) { s16x4 r; asm volatile("ds_read_b64_tr_b16 %0, %1 offset:%2" : "=&v"(r) : "v"(vb), "i"(OFF) : "memory"); return r; }
; #define BARL() asm volatile("s_waitcnt lgkmcnt(0)\n\ts_barrier" ::: "memory")
; #define BARL() asm volatile("s_waitcnt lgkmcnt(0)\n\ts_barrier" ::: "memory")
; template <int D0> __device__ __forceinline__ void pv_one(f32x16& od, unsigned vb, bf16x8 pa0, bf16x8 pa1, bf16x8 pa2, bf16x8 pa3) {
;   const s16x4 l0 = tr_read<v_rd_off(D0, 0, 0)>(vb), h0 = tr_read<v_rd_off(D0, 0, 1)>(vb), l1 = tr_read<v_rd_off(D0, 1, 0)>(vb), h1 = tr_read<v_rd_off(D0, 1, 1)>(vb);
;   const s16x4 l2 = tr_read<v_rd_off(D0, 2, 0)>(vb), h2 = tr_read<v_rd_off(D0, 2, 1)>(vb), l3 = tr_read<v_rd_off(D0, 3, 0)>(vb), h3 = tr_read<v_rd_off(D0, 3, 1)>(vb);
;   asm volatile("s_waitcnt lgkmcnt(0)" ::: "memory"); SBAR();
;     ...
;   od = __builtin_amdgcn_mfma_f32_32x32x16_bf16(pa0, PK(l0, h0), od, 0, 0, 0);
;   od = __builtin_amdgcn_mfma_f32_32x32x16_bf16(pa1, PK(l1, h1), od, 0, 0, 0);
;   od = __builtin_amdgcn_mfma_f32_32x32x16_bf16(pa2, PK(l2, h2), od, 0, 0, 0);
;   od = __builtin_amdgcn_mfma_f32_32x32x16_bf16(pa3, PK(l3, h3), od, 0, 0, 0);
;     ...
; }
; __device__ __forceinline__ void pv_d0(f32x16* o, unsigned vb, bf16x8 pa0, bf16x8 pa1, bf16x8 pa2, bf16x8 pa3) {
;   pv_one<0>(o[0], vb, pa0, pa1, pa2, pa3); pv_one<1>(o[1], vb, pa0, pa1, pa2, pa3); pv_one<2>(o[2], vb, pa0, pa1, pa2, pa3); pv_one<3>(o[3], vb, pa0, pa1, pa2, pa3);
; __device__ __forceinline__ void partialSM(f32x16& p0, f32x16& p1, float& m_reg, float& mn, float& alpha, float cadd) {
;   float pmax = p0[0];
; #pragma unroll
;   for (int r = 1; r < 16; ++r) pmax = fmaxf(pmax, p0[r]);
; #pragma unroll
;   for (int r = 0; r < 16; ++r) pmax = fmaxf(pmax, p1[r]);
;   { auto rr = __builtin_amdgcn_permlane32_swap(__float_as_uint(pmax), __float_as_uint(pmax), false, false);
;     pmax = fmaxf(__uint_as_float(rr[0]), __uint_as_float(rr[1])); }
;   pmax += cadd;
;   if (__builtin_expect(__all(pmax - m_reg <= THRL), 1)) { mn = m_reg; alpha = 1.f; }
;   else { mn = fmaxf(m_reg, pmax); alpha = __builtin_amdgcn_exp2f(m_reg - mn); m_reg = mn; }
; template <int MODE> ...
;     ...
;     pv_d0(o, vb0 + SHM_V, pa0, pa1, pa2, pa3); BIAS(pA0, pA1, (j + 1) * KVBLK, cadd); partialSM(pA0, pA1, m_reg, mnA, alA, cadd);
;     BARL();
	v_mfma_f32_32x32x16_bf16 v[80:95], v[192:195], v[200:203], v[80:95]
	v_mfma_f32_32x32x16_bf16 v[64:79], v[196:199], v[200:203], v[64:79]
	ds_read_b128 v[192:195], v169
	ds_read_b128 v[196:199], v169 offset:4096
	ds_read_b128 v[200:203], v153 offset:1024
	v_cvt_pk_bf16_f32 v138, v217, v181
	v_cvt_pk_bf16_f32 v139, v218, v183
	s_nop 0
	v_permlane32_swap_b32_e32 v136, v138
	v_permlane32_swap_b32_e32 v137, v139
	v_cvt_pk_bf16_f32 v204, v184, v190
	v_cvt_pk_bf16_f32 v205, v191, v219
	s_waitcnt lgkmcnt(0)
	v_mfma_f32_32x32x16_bf16 v[80:95], v[192:195], v[200:203], v[80:95]
	v_mfma_f32_32x32x16_bf16 v[64:79], v[196:199], v[200:203], v[64:79]
	ds_read_b128 v[192:195], v171
	ds_read_b128 v[196:199], v171 offset:4096
	ds_read_b128 v[200:203], v153 offset:2048
	v_cvt_pk_bf16_f32 v206, v206, v207
	v_cvt_pk_bf16_f32 v207, v208, v209
	s_nop 0
	v_permlane32_swap_b32_e32 v204, v206
	v_permlane32_swap_b32_e32 v205, v207
	s_waitcnt lgkmcnt(0)
	v_mfma_f32_32x32x16_bf16 v[80:95], v[192:195], v[200:203], v[80:95]
	v_mfma_f32_32x32x16_bf16 v[64:79], v[196:199], v[200:203], v[64:79]
	ds_read_b128 v[192:195], v173
	ds_read_b128 v[200:203], v173 offset:4096
	ds_read_b128 v[196:199], v153 offset:3072
	s_waitcnt lgkmcnt(0)
	v_mfma_f32_32x32x16_bf16 v[80:95], v[192:195], v[196:199], v[80:95]
	v_mfma_f32_32x32x16_bf16 v[64:79], v[200:203], v[196:199], v[64:79]
	ds_read_b64_tr_b16 v[192:193], v151 offset:0
	ds_read_b64_tr_b16 v[194:195], v151 offset:0x800
	ds_read_b64_tr_b16 v[196:197], v151 offset:0x1000
	ds_read_b64_tr_b16 v[198:199], v151 offset:0x1800
	ds_read_b64_tr_b16 v[200:201], v151 offset:0x2000
	ds_read_b64_tr_b16 v[202:203], v151 offset:0x2800
	ds_read_b64_tr_b16 v[208:209], v151 offset:0x3000
	ds_read_b64_tr_b16 v[210:211], v151 offset:0x3800
	s_waitcnt lgkmcnt(0)
	s_nop 0
	v_mfma_f32_32x32x16_bf16 v[0:15], v[128:131], v[192:195], v[0:15]
	ds_read_b64_tr_b16 v[192:193], v151 offset:0x200
	ds_read_b64_tr_b16 v[194:195], v151 offset:0xa00
	v_mfma_f32_32x32x16_bf16 v[0:15], v[132:135], v[196:199], v[0:15]
	ds_read_b64_tr_b16 v[196:197], v151 offset:0x1200
	ds_read_b64_tr_b16 v[198:199], v151 offset:0x1a00
	v_mfma_f32_32x32x16_bf16 v[0:15], v[136:139], v[200:203], v[0:15]
	ds_read_b64_tr_b16 v[200:201], v151 offset:0x2200
	ds_read_b64_tr_b16 v[202:203], v151 offset:0x2a00
	v_mfma_f32_32x32x16_bf16 v[0:15], v[204:207], v[208:211], v[0:15]
	ds_read_b64_tr_b16 v[208:209], v151 offset:0x3200
	ds_read_b64_tr_b16 v[210:211], v151 offset:0x3a00
	s_waitcnt lgkmcnt(0)
	v_mfma_f32_32x32x16_bf16 v[48:63], v[128:131], v[192:195], v[48:63]
	ds_read_b64_tr_b16 v[192:193], v151 offset:0x400
	ds_read_b64_tr_b16 v[194:195], v151 offset:0xc00
	v_mfma_f32_32x32x16_bf16 v[48:63], v[132:135], v[196:199], v[48:63]
	ds_read_b64_tr_b16 v[196:197], v151 offset:0x1400
	ds_read_b64_tr_b16 v[198:199], v151 offset:0x1c00
	v_mfma_f32_32x32x16_bf16 v[48:63], v[136:139], v[200:203], v[48:63]
	ds_read_b64_tr_b16 v[200:201], v151 offset:0x2400
	ds_read_b64_tr_b16 v[202:203], v151 offset:0x2c00
	v_mfma_f32_32x32x16_bf16 v[48:63], v[204:207], v[208:211], v[48:63]
	ds_read_b64_tr_b16 v[208:209], v151 offset:0x3400
	ds_read_b64_tr_b16 v[210:211], v151 offset:0x3c00
	s_waitcnt lgkmcnt(0)
	v_mfma_f32_32x32x16_bf16 v[32:47], v[128:131], v[192:195], v[32:47]
	ds_read_b64_tr_b16 v[192:193], v151 offset:0x600
	ds_read_b64_tr_b16 v[194:195], v151 offset:0xe00
	v_mfma_f32_32x32x16_bf16 v[32:47], v[132:135], v[196:199], v[32:47]
	ds_read_b64_tr_b16 v[196:197], v151 offset:0x1600
	ds_read_b64_tr_b16 v[198:199], v151 offset:0x1e00
	v_mfma_f32_32x32x16_bf16 v[32:47], v[136:139], v[200:203], v[32:47]
	ds_read_b64_tr_b16 v[200:201], v151 offset:0x2600
	ds_read_b64_tr_b16 v[202:203], v151 offset:0x2e00
	v_mfma_f32_32x32x16_bf16 v[32:47], v[204:207], v[208:211], v[32:47]
	ds_read_b64_tr_b16 v[208:209], v151 offset:0x3600
	ds_read_b64_tr_b16 v[210:211], v151 offset:0x3e00
	s_waitcnt lgkmcnt(0)
	v_mfma_f32_32x32x16_bf16 v[16:31], v[128:131], v[192:195], v[16:31]
	v_max_f32_e32 v128, v80, v81
	v_max3_f32 v128, v128, v82, v83
	v_max3_f32 v128, v128, v84, v85
	v_max3_f32 v128, v128, v86, v87
	v_max3_f32 v128, v128, v88, v89
	v_max3_f32 v128, v128, v90, v91
	v_max3_f32 v128, v128, v92, v93
	v_max3_f32 v128, v128, v94, v95
	v_max3_f32 v128, v128, v64, v65
	v_max3_f32 v128, v128, v66, v67
	v_max3_f32 v128, v128, v68, v69
	v_max3_f32 v128, v128, v70, v71
	v_max3_f32 v128, v128, v72, v73
	v_max3_f32 v128, v128, v74, v75
	v_max3_f32 v128, v128, v76, v77
	v_max3_f32 v128, v128, v78, v79
	v_mfma_f32_32x32x16_bf16 v[16:31], v[132:135], v[196:199], v[16:31]
	v_mov_b32_e32 v129, v128
	s_nop 1
	v_permlane32_swap_b32_e32 v128, v129
	v_max_f32_e32 v128, v128, v129
	v_sub_f32_e32 v129, v128, v145
	v_cmp_ge_f32_e32 vcc, s94, v129
	s_cmp_eq_u64 vcc, exec
	v_mfma_f32_32x32x16_bf16 v[16:31], v[136:139], v[200:203], v[16:31]
	s_cselect_b64 s[40:41], -1, 0
	s_min_u32 s12, s26, 60
	s_add_i32 s31, s12, 3
	s_lshl_b32 s12, s31, 18
	s_add_u32 s12, s6, s12
	s_waitcnt lgkmcnt(0)
	s_barrier
; #define DMA_K(t, b) do { const char* kb_ = (const char*)Kh + (size_t)(t) * (KVBLK * LDX * 2); \
;     dma16(kb_, voffK, ldsb + K_OFF + (b) * SHM_K + wid * 1024); dma16(kb_ + 32 * LDX * 2, voffK, ldsb + K_OFF + (b) * SHM_K + (wid + 8) * 1024); \
;     if constexpr (MODE == 0) dma16((const char*)Krh + (size_t)(t) * (KVBLK * 128), voffR, ldsb + KR_OFF + (b) * 8192 + wid * 1024); } while (0)
; #define DMA_V(t, b) do { const char* vb_ = (const char*)Vh + (size_t)(t) * (KVBLK * LDX * 2); \
;     dma16(vb_, voffV, ldsb + V_OFF + (b) * SHM_V + wid * 1024); dma16(vb_ + 32 * LDX * 2, voffV, ldsb + V_OFF + (b) * SHM_V + (wid + 8) * 1024); } while (0)
; #define WAITV() do { if constexpr (MODE == 0) asm volatile("s_waitcnt vmcnt(5)" ::: "memory"); else asm volatile("s_waitcnt vmcnt(4)" ::: "memory"); } while (0)
; #define BARL() asm volatile("s_waitcnt lgkmcnt(0)\n\ts_barrier" ::: "memory")
; #define RESC(a) do { if (__any((a) < 1.f)) { if (hi == 0) al_l[r32] = (a); asm volatile("s_waitcnt lgkmcnt(0)" ::: "memory"); \
;     _Pragma("unroll") for (int d = 0; d < 4; ++d) _Pragma("unroll") for (int r = 0; r < 16; ++r) o[d][r] *= al_l[crow(r, hi)]; } } while (0)
; #define BARL() asm volatile("s_waitcnt lgkmcnt(0)\n\ts_barrier" ::: "memory")
; __device__ __forceinline__ void partialSM(f32x16& p0, f32x16& p1, float& m_reg, float& mn, float& alpha, float cadd) {
;     ...
;   const float off = cadd - mn;
; #pragma unroll
;   for (int r = 0; r < 16; ++r) p0[r] += off;
; #pragma unroll
;   for (int r = 0; r < 16; ++r) p1[r] += off;
; #pragma unroll
;   for (int r = 0; r < 16; ++r) p0[r] = __builtin_amdgcn_exp2f(p0[r]);
; }
; __device__ __forceinline__ void finishSM(f32x16& p0, f32x16& p1, float alpha, float& l_reg, bf16x8& pa0, bf16x8& pa1, bf16x8& pa2, bf16x8& pa3) {
;     ...
;   l_reg = l_reg * alpha + ps;
; template <int MODE> ...
;     ...
;     { const int tk = (j + 3 < NT) ? j + 3 : NT - 1; DMA_K(tk, 0); } DMA_V(j + 2, 1);
;     WAITV();
;     RESC(alA); BARL();
	s_addc_u32 s13, s7, 0
	s_mov_b32 m0, s22
	s_nop 0
	global_load_lds_dwordx4 v155, s[12:13]
	s_add_u32 s12, s12, 0x20000
	s_addc_u32 s13, s13, 0
	s_mov_b32 m0, s2
	s_nop 0
	global_load_lds_dwordx4 v155, s[12:13]
	s_lshl_b32 s12, s31, 13
	v_max_f32_e32 v129, v145, v145
	s_add_u32 s12, s8, s12
	v_mfma_f32_32x32x16_bf16 v[16:31], v[204:207], v[208:211], v[16:31]
	v_max_f32_e32 v128, v129, v128
	s_addc_u32 s13, s9, 0
	v_sub_f32_e32 v129, v145, v128
	s_mov_b32 m0, s95
	s_nop 0
	global_load_lds_dwordx4 v157, s[12:13]
	s_add_u32 s12, s27, 0x314c0000
	v_exp_f32_e32 v129, v129
	s_addc_u32 s13, s30, 0
	s_mov_b32 m0, s1
	s_nop 0
	global_load_lds_dwordx4 v156, s[12:13]
	s_add_u32 s12, s27, 0x314e0000
	s_addc_u32 s13, s30, 0
	s_mov_b32 m0, s69
	s_nop 0
	global_load_lds_dwordx4 v156, s[12:13]
	s_waitcnt vmcnt(5)
	v_cndmask_b32_e64 v181, v129, 1.0, s[40:41]
	v_cmp_gt_f32_e32 vcc, 1.0, v181
	s_cbranch_vccz .LBB0_947
	s_and_saveexec_b64 s[12:13], s[38:39]
	ds_write_b32 v154, v181
	s_or_b64 exec, exec, s[12:13]
	v_readlane_b32 s12, v253, 45
	s_waitcnt lgkmcnt(0)
	s_nop 1
	v_add_u32_e32 v129, s12, v140
	v_readlane_b32 s12, v253, 46
	s_nop 1
	v_add_u32_e32 v134, s12, v140
	v_readlane_b32 s12, v253, 44
	ds_read_b128 v[130:133], v129
	ds_read_b128 v[134:137], v134
	v_add_u32_e32 v129, s12, v140
	v_readlane_b32 s12, v253, 43
	ds_read_b128 v[192:195], v129
	s_waitcnt lgkmcnt(2)
	v_pk_mul_f32 v[8:9], v[8:9], v[130:131]
	v_add_u32_e32 v129, s12, v140
	ds_read_b128 v[196:199], v129
	s_waitcnt lgkmcnt(2)
	v_pk_mul_f32 v[12:13], v[12:13], v[134:135]
	s_waitcnt lgkmcnt(1)
	v_pk_mul_f32 v[4:5], v[4:5], v[192:193]
	v_pk_mul_f32 v[14:15], v[14:15], v[136:137]
	v_pk_mul_f32 v[10:11], v[10:11], v[132:133]
	v_pk_mul_f32 v[6:7], v[6:7], v[194:195]
	s_waitcnt lgkmcnt(0)
	v_pk_mul_f32 v[2:3], v[2:3], v[198:199]
	v_pk_mul_f32 v[0:1], v[0:1], v[196:197]
	v_pk_mul_f32 v[60:61], v[134:135], v[60:61]
	v_pk_mul_f32 v[56:57], v[130:131], v[56:57]
	v_pk_mul_f32 v[52:53], v[192:193], v[52:53]
	v_pk_mul_f32 v[62:63], v[136:137], v[62:63]
	v_pk_mul_f32 v[58:59], v[132:133], v[58:59]
	v_pk_mul_f32 v[54:55], v[194:195], v[54:55]
	v_pk_mul_f32 v[50:51], v[198:199], v[50:51]
	v_pk_mul_f32 v[48:49], v[196:197], v[48:49]
	v_pk_mul_f32 v[44:45], v[134:135], v[44:45]
	v_pk_mul_f32 v[40:41], v[130:131], v[40:41]
	v_pk_mul_f32 v[36:37], v[192:193], v[36:37]
	v_pk_mul_f32 v[46:47], v[136:137], v[46:47]
	v_pk_mul_f32 v[42:43], v[132:133], v[42:43]
	v_pk_mul_f32 v[38:39], v[194:195], v[38:39]
	v_pk_mul_f32 v[34:35], v[198:199], v[34:35]
	v_pk_mul_f32 v[32:33], v[196:197], v[32:33]
	v_pk_mul_f32 v[28:29], v[134:135], v[28:29]
	v_pk_mul_f32 v[24:25], v[130:131], v[24:25]
	v_pk_mul_f32 v[20:21], v[192:193], v[20:21]
	v_pk_mul_f32 v[30:31], v[136:137], v[30:31]
	v_pk_mul_f32 v[26:27], v[132:133], v[26:27]
	v_pk_mul_f32 v[22:23], v[194:195], v[22:23]
	v_pk_mul_f32 v[18:19], v[198:199], v[18:19]
	v_pk_mul_f32 v[16:17], v[196:197], v[16:17]
.LBB0_947:
	v_add_f32_e32 v129, v142, v143
	s_add_u32 s24, s24, 0x80000
	v_fmac_f32_e32 v129, v176, v141
	v_add_f32_e32 v141, v174, v182
	v_cndmask_b32_e64 v174, v128, v145, s[40:41]
	s_addc_u32 s25, s25, 0
	v_add_f32_e64 v80, v80, -v174
	v_add_f32_e64 v81, v81, -v174
	v_add_f32_e64 v82, v82, -v174
	v_add_f32_e64 v83, v83, -v174
	v_add_f32_e64 v84, v84, -v174
	v_add_f32_e64 v85, v85, -v174
	v_add_f32_e64 v86, v86, -v174
	v_add_f32_e64 v87, v87, -v174
	v_add_f32_e64 v88, v88, -v174
	v_add_f32_e64 v89, v89, -v174
	v_add_f32_e64 v90, v90, -v174
	v_add_f32_e64 v91, v91, -v174
	v_add_f32_e64 v92, v92, -v174
	v_add_f32_e64 v93, v93, -v174
	v_add_f32_e64 v94, v94, -v174
	v_add_f32_e64 v95, v95, -v174
	s_add_u32 s10, s10, 0x4000
	v_exp_f32_e32 v197, v80
	v_exp_f32_e32 v198, v81
	v_exp_f32_e32 v199, v82
	v_exp_f32_e32 v201, v83
	v_exp_f32_e32 v202, v84
	v_exp_f32_e32 v204, v85
	v_exp_f32_e32 v200, v86
	v_exp_f32_e32 v203, v87
	v_exp_f32_e32 v193, v88
	v_exp_f32_e32 v194, v89
	v_exp_f32_e32 v195, v90
	v_exp_f32_e32 v196, v91
	v_exp_f32_e32 v182, v92
	v_exp_f32_e32 v183, v93
	v_exp_f32_e32 v184, v94
	v_exp_f32_e32 v192, v95
	s_addc_u32 s11, s11, 0
	s_add_u32 s19, s19, 0x80000
	v_sub_f32_e32 v134, 0, v174
	v_fmac_f32_e32 v141, v129, v144
	v_add_f32_e32 v144, v64, v134
	v_add_f32_e32 v145, v65, v134
	v_add_f32_e32 v142, v66, v134
	v_add_f32_e32 v143, v67, v134
	v_add_f32_e32 v138, v68, v134
	v_add_f32_e32 v139, v69, v134
	v_add_f32_e32 v136, v70, v134
	v_add_f32_e32 v137, v71, v134
	v_add_f32_e32 v130, v72, v134
	v_add_f32_e32 v131, v73, v134
	v_add_f32_e32 v128, v74, v134
	v_add_f32_e32 v129, v75, v134
	v_add_f32_e32 v132, v76, v134
	v_add_f32_e32 v133, v77, v134
	v_add_f32_e32 v135, v79, v134
	v_add_f32_e32 v134, v78, v134
	s_waitcnt lgkmcnt(0)
	s_barrier
	s_addc_u32 s21, s21, 0
	s_cmp_gt_u32 s26, 60
	s_cbranch_scc1 .LBB0_949
	v_mov_b32_e32 v176, v181
	s_branch .LBB0_939
